# non-temporal hint on the once-read f32 weight loads of the transpose/convert tiles
# baseline (speedup 1.0000x reference)
; __device__ __forceinline__ void convT_tile(const float* __restrict__ W, int K, int N, bf16_t* __restrict__ WT, int tile, unsigned char* shm, int wave, int lane) {
;     const int ntn = N / 64, k0 = (tile / ntn) * 64, n0 = (tile % ntn) * 64;
;     float* T = (float*)shm + wave * (64 * 65);
;     { const int r4 = lane >> 4, c4 = (lane & 15) * 4;
; #pragma unroll
;       for (int i = 0; i < 16; ++i) { const int rr = 4 * i + r4; const float4 v = *(const float4*)(W + (size_t)(k0 + rr) * N + n0 + c4);
;           T[rr * 65 + c4] = v.x; T[rr * 65 + c4 + 1] = v.y; T[rr * 65 + c4 + 2] = v.z; T[rr * 65 + c4 + 3] = v.w; } }
.LBB0_196:
	v_cmp_lt_i32_e32 vcc, s19, v58
	s_and_saveexec_b64 s[6:7], vcc
	s_xor_b64 s[6:7], exec, s[6:7]
	s_cbranch_execz .LBB0_210
	v_cmp_lt_u32_e32 vcc, s20, v58
	s_and_saveexec_b64 s[8:9], vcc
	s_xor_b64 s[8:9], exec, s[8:9]
	s_cbranch_execz .LBB0_207
	v_cmp_lt_u32_e32 vcc, s21, v58
	s_and_saveexec_b64 s[10:11], vcc
	s_xor_b64 s[10:11], exec, s[10:11]
	s_cbranch_execz .LBB0_204
	v_cmp_lt_u32_e32 vcc, s22, v58
	s_and_saveexec_b64 s[16:17], vcc
	s_xor_b64 s[16:17], exec, s[16:17]
	s_cbranch_execz .LBB0_201
	v_and_b32_e32 v124, 0x1c0, v30
	v_and_b32_e32 v59, 0x7c0, v56
	v_lshlrev_b32_e32 v4, 2, v124
	v_lshl_add_u64 v[120:121], v[6:7], 0, v[4:5]
	v_or_b32_e32 v4, v59, v1
	v_lshlrev_b32_e32 v4, 11, v4
	v_lshl_add_u64 v[68:69], v[120:121], 0, v[4:5]
	v_or_b32_e32 v4, v59, v27
	v_lshlrev_b32_e32 v4, 11, v4
	v_lshl_add_u64 v[70:71], v[120:121], 0, v[4:5]
	v_or_b32_e32 v4, v59, v31
	v_lshlrev_b32_e32 v4, 11, v4
	v_lshl_add_u64 v[76:77], v[120:121], 0, v[4:5]
	v_or_b32_e32 v4, v59, v32
	v_lshlrev_b32_e32 v4, 11, v4
	v_lshl_add_u64 v[78:79], v[120:121], 0, v[4:5]
	v_or_b32_e32 v4, v59, v33
	v_lshlrev_b32_e32 v4, 11, v4
	v_lshl_add_u64 v[84:85], v[120:121], 0, v[4:5]
	v_or_b32_e32 v4, v59, v34
	v_lshlrev_b32_e32 v4, 11, v4
	v_lshl_add_u64 v[86:87], v[120:121], 0, v[4:5]
	v_or_b32_e32 v4, v59, v36
	v_lshlrev_b32_e32 v4, 11, v4
	global_load_dwordx4 v[60:63], v[68:69], off nt
	global_load_dwordx4 v[64:67], v[70:71], off nt
	s_nop 0
	global_load_dwordx4 v[68:71], v[76:77], off nt
	global_load_dwordx4 v[72:75], v[78:79], off nt
	s_nop 0
	global_load_dwordx4 v[76:79], v[84:85], off nt
	global_load_dwordx4 v[80:83], v[86:87], off nt
	v_lshl_add_u64 v[84:85], v[120:121], 0, v[4:5]
	v_or_b32_e32 v4, v59, v37
	global_load_dwordx4 v[84:87], v[84:85], off nt
	v_lshlrev_b32_e32 v4, 11, v4
	v_lshl_add_u64 v[88:89], v[120:121], 0, v[4:5]
	v_or_b32_e32 v4, v59, v38
	global_load_dwordx4 v[88:91], v[88:89], off nt
	v_lshlrev_b32_e32 v4, 11, v4
	v_lshl_add_u64 v[92:93], v[120:121], 0, v[4:5]
	v_or_b32_e32 v4, v59, v39
	global_load_dwordx4 v[92:95], v[92:93], off nt
	v_lshlrev_b32_e32 v4, 11, v4
	v_lshl_add_u64 v[96:97], v[120:121], 0, v[4:5]
	v_or_b32_e32 v4, v59, v40
	global_load_dwordx4 v[96:99], v[96:97], off nt
	v_lshlrev_b32_e32 v4, 11, v4
	v_lshl_add_u64 v[100:101], v[120:121], 0, v[4:5]
	v_or_b32_e32 v4, v59, v42
	global_load_dwordx4 v[100:103], v[100:101], off nt
	v_lshlrev_b32_e32 v4, 11, v4
	v_lshl_add_u64 v[104:105], v[120:121], 0, v[4:5]
	v_or_b32_e32 v4, v59, v43
	global_load_dwordx4 v[104:107], v[104:105], off nt
	v_lshlrev_b32_e32 v4, 11, v4
	v_lshl_add_u64 v[108:109], v[120:121], 0, v[4:5]
	v_or_b32_e32 v4, v59, v44
	global_load_dwordx4 v[108:111], v[108:109], off nt
	v_lshlrev_b32_e32 v4, 11, v4
	v_lshl_add_u64 v[112:113], v[120:121], 0, v[4:5]
	v_or_b32_e32 v4, v59, v45
	global_load_dwordx4 v[112:115], v[112:113], off nt
	v_lshlrev_b32_e32 v4, 11, v4
	v_lshl_add_u64 v[116:117], v[120:121], 0, v[4:5]
	v_or_b32_e32 v4, v59, v46
	global_load_dwordx4 v[116:119], v[116:117], off nt
	v_lshlrev_b32_e32 v4, 11, v4
	v_lshl_add_u64 v[120:121], v[120:121], 0, v[4:5]
	global_load_dwordx4 v[120:123], v[120:121], off nt
	v_add_u32_e32 v4, v3, v25
	v_add_u32_e32 v125, v3, v35
	v_add_u32_e32 v126, 0x410, v4
	v_add_u32_e32 v127, 0x418, v4
	v_add_u32_e32 v128, 0x820, v4
	v_add_u32_e32 v129, 0x828, v4
	v_add_u32_e32 v130, 0xc30, v4
	v_add_u32_e32 v131, 0xc38, v4
	v_add_u32_e32 v132, 0x1040, v4
	v_add_u32_e32 v133, 0x1048, v4
	v_add_u32_e32 v134, 0x1450, v4
	s_waitcnt vmcnt(15)
	ds_write2_b32 v4, v60, v61 offset1:1
	ds_write2_b32 v4, v62, v63 offset0:2 offset1:3
	s_waitcnt vmcnt(14)
	ds_write2_b32 v126, v64, v65 offset1:1
	ds_write2_b32 v127, v66, v67 offset1:1
	s_waitcnt vmcnt(13)
	ds_write2_b32 v128, v68, v69 offset1:1
	ds_write2_b32 v129, v70, v71 offset1:1
	s_waitcnt vmcnt(12)
	ds_write2_b32 v130, v72, v73 offset1:1
	ds_write2_b32 v131, v74, v75 offset1:1
	s_waitcnt vmcnt(11)
	ds_write2_b32 v132, v76, v77 offset1:1
	ds_write2_b32 v133, v78, v79 offset1:1
	s_waitcnt vmcnt(10)
	ds_write2_b32 v134, v80, v81 offset1:1
	ds_write2_b32 v125, v82, v83 offset0:2 offset1:3
	v_add_u32_e32 v4, 0x410, v125
	s_waitcnt vmcnt(9)
	ds_write2_b32 v4, v84, v85 offset1:1
	v_add_u32_e32 v4, 0x418, v125
	ds_write2_b32 v4, v86, v87 offset1:1
	v_add_u32_e32 v4, 0x820, v125
	s_waitcnt vmcnt(8)
	ds_write2_b32 v4, v88, v89 offset1:1
	v_add_u32_e32 v4, 0x828, v125
	ds_write2_b32 v4, v90, v91 offset1:1
	v_add_u32_e32 v4, 0xc30, v125
	s_waitcnt vmcnt(7)
	ds_write2_b32 v4, v92, v93 offset1:1
	v_add_u32_e32 v4, 0xc38, v125
	ds_write2_b32 v4, v94, v95 offset1:1
	v_add_u32_e32 v4, 0x1040, v125
	s_waitcnt vmcnt(6)
	ds_write2_b32 v4, v96, v97 offset1:1
	v_add_u32_e32 v4, 0x1048, v125
	ds_write2_b32 v4, v98, v99 offset1:1
	v_add_u32_e32 v4, 0x1450, v125
	s_waitcnt vmcnt(5)
	ds_write2_b32 v4, v100, v101 offset1:1
	v_add_u32_e32 v4, v3, v41
	v_add_u32_e32 v60, 0x410, v4
	ds_write2_b32 v4, v102, v103 offset0:2 offset1:3
	s_waitcnt vmcnt(4)
	ds_write2_b32 v60, v104, v105 offset1:1
	v_add_u32_e32 v60, 0x418, v4
	ds_write2_b32 v60, v106, v107 offset1:1
	v_add_u32_e32 v60, 0x820, v4
	s_waitcnt vmcnt(3)
	ds_write2_b32 v60, v108, v109 offset1:1
	v_add_u32_e32 v60, 0x828, v4
	ds_write2_b32 v60, v110, v111 offset1:1
	v_add_u32_e32 v60, 0xc30, v4
	s_waitcnt vmcnt(2)
	ds_write2_b32 v60, v112, v113 offset1:1
	v_add_u32_e32 v60, 0xc38, v4
	ds_write2_b32 v60, v114, v115 offset1:1
	v_add_u32_e32 v60, 0x1040, v4
	s_waitcnt vmcnt(1)
	ds_write2_b32 v60, v116, v117 offset1:1
	v_add_u32_e32 v60, 0x1048, v4
	ds_write2_b32 v60, v118, v119 offset1:1
	v_add_u32_e32 v60, 0x1450, v4
	v_add_u32_e32 v4, 0x1458, v4
	s_waitcnt vmcnt(0)
; __device__ __forceinline__ unsigned cvt_pk_bf16(float lo, float hi) { unsigned r; asm("v_cvt_pk_bf16_f32 %0, %1, %2" : "=v"(r) : "v"(lo), "v"(hi)); return r; }
; __device__ __forceinline__ void convT_tile(const float* __restrict__ W, int K, int N, bf16_t* __restrict__ WT, int tile, unsigned char* shm, int wave, int lane) {
;     ...
;     { const int n8 = lane >> 3, k8 = (lane & 7) * 8;
; #pragma unroll
;       for (int i = 0; i < 8; ++i) { const int n = 8 * i + n8; const float* sp = T + k8 * 65 + n;
;           u32x4 o; o.x = cvt_pk_bf16(sp[0], sp[65]); o.y = cvt_pk_bf16(sp[2 * 65], sp[3 * 65]); o.z = cvt_pk_bf16(sp[4 * 65], sp[5 * 65]); o.w = cvt_pk_bf16(sp[6 * 65], sp[7 * 65]);
;           *(u32x4*)(WT + (size_t)(n0 + n) * K + k0 + k8) = o; } }
;     __builtin_amdgcn_fence(__ATOMIC_RELEASE, "wavefront"); __builtin_amdgcn_wave_barrier(); __builtin_amdgcn_fence(__ATOMIC_ACQUIRE, "wavefront");
	ds_write2_b32 v4, v122, v123 offset1:1
	v_lshlrev_b32_e32 v4, 1, v59
	v_add_u32_e32 v59, 0x400, v48
	ds_write2_b32 v60, v120, v121 offset1:1
	ds_read2_b32 v[64:65], v48 offset0:65 offset1:73
	ds_read2_b32 v[66:67], v48 offset1:8
	ds_read2_b32 v[68:69], v48 offset0:130 offset1:138
	ds_read2_b32 v[70:71], v48 offset0:195 offset1:203
	ds_read2_b32 v[72:73], v59 offset0:4 offset1:12
	ds_read2_b32 v[74:75], v59 offset0:69 offset1:77
	ds_read2_b32 v[76:77], v59 offset0:134 offset1:142
	ds_read2_b32 v[78:79], v59 offset0:199 offset1:207
	v_lshl_add_u64 v[80:81], v[10:11], 0, v[4:5]
	v_or_b32_e32 v4, v124, v47
	v_lshlrev_b32_e32 v4, 10, v4
	v_lshl_add_u64 v[82:83], v[80:81], 0, v[4:5]
	s_waitcnt lgkmcnt(6)
	v_cvt_pk_bf16_f32 v60, v66, v64
	s_waitcnt lgkmcnt(4)
	v_cvt_pk_bf16_f32 v61, v68, v70
	s_waitcnt lgkmcnt(2)
	v_cvt_pk_bf16_f32 v62, v72, v74
	s_waitcnt lgkmcnt(0)
	v_cvt_pk_bf16_f32 v63, v76, v78
	global_store_dwordx4 v[82:83], v[60:63], off
	v_or_b32_e32 v4, v124, v49
	v_lshlrev_b32_e32 v4, 10, v4
	v_cvt_pk_bf16_f32 v60, v67, v65
	v_cvt_pk_bf16_f32 v61, v69, v71
	v_cvt_pk_bf16_f32 v62, v73, v75
	v_cvt_pk_bf16_f32 v63, v77, v79
	ds_read2_b32 v[66:67], v48 offset0:16 offset1:24
	ds_read2_b32 v[68:69], v48 offset0:81 offset1:89
	ds_read2_b32 v[70:71], v48 offset0:146 offset1:154
	ds_read2_b32 v[72:73], v48 offset0:211 offset1:219
	ds_read2_b32 v[74:75], v59 offset0:20 offset1:28
	ds_read2_b32 v[76:77], v59 offset0:85 offset1:93
	ds_read2_b32 v[78:79], v59 offset0:150 offset1:158
	ds_read2_b32 v[82:83], v59 offset0:215 offset1:223
	v_lshl_add_u64 v[64:65], v[80:81], 0, v[4:5]
	v_or_b32_e32 v4, v124, v50
	v_lshlrev_b32_e32 v4, 10, v4
	global_store_dwordx4 v[64:65], v[60:63], off
	v_lshl_add_u64 v[64:65], v[80:81], 0, v[4:5]
	v_or_b32_e32 v4, v124, v51
	s_waitcnt lgkmcnt(6)
	v_cvt_pk_bf16_f32 v60, v66, v68
	s_waitcnt lgkmcnt(4)
	v_cvt_pk_bf16_f32 v61, v70, v72
	s_waitcnt lgkmcnt(2)
	v_cvt_pk_bf16_f32 v62, v74, v76
	s_waitcnt lgkmcnt(0)
	v_cvt_pk_bf16_f32 v63, v78, v82
	global_store_dwordx4 v[64:65], v[60:63], off
	v_lshlrev_b32_e32 v4, 10, v4
	v_lshl_add_u64 v[64:65], v[80:81], 0, v[4:5]
	v_cvt_pk_bf16_f32 v60, v67, v69
	v_cvt_pk_bf16_f32 v61, v71, v73
	v_cvt_pk_bf16_f32 v62, v75, v77
	v_cvt_pk_bf16_f32 v63, v79, v83
	ds_read2_b32 v[66:67], v48 offset0:32 offset1:40
	ds_read2_b32 v[68:69], v48 offset0:97 offset1:105
	ds_read2_b32 v[70:71], v48 offset0:162 offset1:170
	ds_read2_b32 v[72:73], v48 offset0:227 offset1:235
	ds_read2_b32 v[74:75], v59 offset0:36 offset1:44
	ds_read2_b32 v[76:77], v59 offset0:101 offset1:109
	ds_read2_b32 v[78:79], v59 offset0:166 offset1:174
	ds_read2_b32 v[82:83], v59 offset0:231 offset1:239
	v_or_b32_e32 v4, v124, v52
	v_lshlrev_b32_e32 v4, 10, v4
	global_store_dwordx4 v[64:65], v[60:63], off
	v_lshl_add_u64 v[64:65], v[80:81], 0, v[4:5]
	v_or_b32_e32 v4, v124, v53
	s_waitcnt lgkmcnt(6)
	v_cvt_pk_bf16_f32 v60, v66, v68
	s_waitcnt lgkmcnt(4)
	v_cvt_pk_bf16_f32 v61, v70, v72
	s_waitcnt lgkmcnt(2)
	v_cvt_pk_bf16_f32 v62, v74, v76
	s_waitcnt lgkmcnt(0)
	v_cvt_pk_bf16_f32 v63, v78, v82
	global_store_dwordx4 v[64:65], v[60:63], off
	v_lshlrev_b32_e32 v4, 10, v4
	v_lshl_add_u64 v[64:65], v[80:81], 0, v[4:5]
	v_cvt_pk_bf16_f32 v60, v67, v69
	v_cvt_pk_bf16_f32 v61, v71, v73
	v_cvt_pk_bf16_f32 v62, v75, v77
	v_cvt_pk_bf16_f32 v63, v79, v83
	ds_read2_b32 v[66:67], v48 offset0:48 offset1:56
	ds_read2_b32 v[68:69], v48 offset0:113 offset1:121
	ds_read2_b32 v[70:71], v48 offset0:178 offset1:186
	ds_read2_b32 v[72:73], v48 offset0:243 offset1:251
	ds_read2_b32 v[74:75], v59 offset0:52 offset1:60
	ds_read2_b32 v[76:77], v59 offset0:117 offset1:125
	ds_read2_b32 v[78:79], v59 offset0:182 offset1:190
	ds_read2_b32 v[82:83], v59 offset0:247 offset1:255
	v_or_b32_e32 v4, v124, v54
	v_lshlrev_b32_e32 v4, 10, v4
	global_store_dwordx4 v[64:65], v[60:63], off
	v_lshl_add_u64 v[64:65], v[80:81], 0, v[4:5]
	v_or_b32_e32 v4, v124, v55
	v_lshlrev_b32_e32 v4, 10, v4
	s_waitcnt lgkmcnt(6)
	v_cvt_pk_bf16_f32 v60, v66, v68
	s_waitcnt lgkmcnt(4)
	v_cvt_pk_bf16_f32 v61, v70, v72
	s_waitcnt lgkmcnt(2)
	v_cvt_pk_bf16_f32 v62, v74, v76
	s_waitcnt lgkmcnt(0)
	v_cvt_pk_bf16_f32 v63, v78, v82
	global_store_dwordx4 v[64:65], v[60:63], off
	v_lshl_add_u64 v[64:65], v[80:81], 0, v[4:5]
	s_nop 0
	v_cvt_pk_bf16_f32 v60, v67, v69
	v_cvt_pk_bf16_f32 v61, v71, v73
	v_cvt_pk_bf16_f32 v62, v75, v77
	v_cvt_pk_bf16_f32 v63, v79, v83
	global_store_dwordx4 v[64:65], v[60:63], off
; __device__ __forceinline__ void convT_tile(const float* __restrict__ W, int K, int N, bf16_t* __restrict__ WT, int tile, unsigned char* shm, int wave, int lane) {
;     const int ntn = N / 64, k0 = (tile / ntn) * 64, n0 = (tile % ntn) * 64;
;     float* T = (float*)shm + wave * (64 * 65);
;     { const int r4 = lane >> 4, c4 = (lane & 15) * 4;
; #pragma unroll
;       for (int i = 0; i < 16; ++i) { const int rr = 4 * i + r4; const float4 v = *(const float4*)(W + (size_t)(k0 + rr) * N + n0 + c4);
;           T[rr * 65 + c4] = v.x; T[rr * 65 + c4 + 1] = v.y; T[rr * 65 + c4 + 2] = v.z; T[rr * 65 + c4 + 3] = v.w; } }
.LBB0_201:
	s_andn2_saveexec_b64 s[16:17], s[16:17]
	s_cbranch_execz .LBB0_203
	v_and_b32_e32 v124, 0x7c0, v30
	v_and_b32_e32 v59, 0x1ffc0, v57
	v_lshlrev_b32_e32 v4, 2, v124
	v_lshl_add_u64 v[120:121], v[12:13], 0, v[4:5]
	v_or_b32_e32 v4, v59, v1
	v_lshlrev_b32_e32 v4, 13, v4
	v_lshl_add_u64 v[68:69], v[120:121], 0, v[4:5]
	v_or_b32_e32 v4, v59, v27
	v_lshlrev_b32_e32 v4, 13, v4
	v_lshl_add_u64 v[70:71], v[120:121], 0, v[4:5]
	v_or_b32_e32 v4, v59, v31
	v_lshlrev_b32_e32 v4, 13, v4
	v_lshl_add_u64 v[76:77], v[120:121], 0, v[4:5]
	v_or_b32_e32 v4, v59, v32
	v_lshlrev_b32_e32 v4, 13, v4
	v_lshl_add_u64 v[78:79], v[120:121], 0, v[4:5]
	v_or_b32_e32 v4, v59, v33
	v_lshlrev_b32_e32 v4, 13, v4
	v_lshl_add_u64 v[84:85], v[120:121], 0, v[4:5]
	v_or_b32_e32 v4, v59, v34
	v_lshlrev_b32_e32 v4, 13, v4
	v_lshl_add_u64 v[86:87], v[120:121], 0, v[4:5]
	v_or_b32_e32 v4, v59, v36
	v_lshlrev_b32_e32 v4, 13, v4
	global_load_dwordx4 v[60:63], v[68:69], off nt
	global_load_dwordx4 v[64:67], v[70:71], off nt
	s_nop 0
	global_load_dwordx4 v[68:71], v[76:77], off nt
	global_load_dwordx4 v[72:75], v[78:79], off nt
	s_nop 0
	global_load_dwordx4 v[76:79], v[84:85], off nt
	global_load_dwordx4 v[80:83], v[86:87], off nt
	v_lshl_add_u64 v[84:85], v[120:121], 0, v[4:5]
	v_or_b32_e32 v4, v59, v37
	global_load_dwordx4 v[84:87], v[84:85], off nt
	v_lshlrev_b32_e32 v4, 13, v4
	v_lshl_add_u64 v[88:89], v[120:121], 0, v[4:5]
	v_or_b32_e32 v4, v59, v38
	global_load_dwordx4 v[88:91], v[88:89], off nt
	v_lshlrev_b32_e32 v4, 13, v4
	v_lshl_add_u64 v[92:93], v[120:121], 0, v[4:5]
	v_or_b32_e32 v4, v59, v39
	global_load_dwordx4 v[92:95], v[92:93], off nt
	v_lshlrev_b32_e32 v4, 13, v4
	v_lshl_add_u64 v[96:97], v[120:121], 0, v[4:5]
	v_or_b32_e32 v4, v59, v40
	global_load_dwordx4 v[96:99], v[96:97], off nt
	v_lshlrev_b32_e32 v4, 13, v4
	v_lshl_add_u64 v[100:101], v[120:121], 0, v[4:5]
	v_or_b32_e32 v4, v59, v42
	global_load_dwordx4 v[100:103], v[100:101], off nt
	v_lshlrev_b32_e32 v4, 13, v4
	v_lshl_add_u64 v[104:105], v[120:121], 0, v[4:5]
	v_or_b32_e32 v4, v59, v43
	global_load_dwordx4 v[104:107], v[104:105], off nt
	v_lshlrev_b32_e32 v4, 13, v4
	v_lshl_add_u64 v[108:109], v[120:121], 0, v[4:5]
	v_or_b32_e32 v4, v59, v44
	global_load_dwordx4 v[108:111], v[108:109], off nt
	v_lshlrev_b32_e32 v4, 13, v4
	v_lshl_add_u64 v[112:113], v[120:121], 0, v[4:5]
	v_or_b32_e32 v4, v59, v45
	global_load_dwordx4 v[112:115], v[112:113], off nt
	v_lshlrev_b32_e32 v4, 13, v4
	v_lshl_add_u64 v[116:117], v[120:121], 0, v[4:5]
	v_or_b32_e32 v4, v59, v46
	global_load_dwordx4 v[116:119], v[116:117], off nt
	v_lshlrev_b32_e32 v4, 13, v4
	v_lshl_add_u64 v[120:121], v[120:121], 0, v[4:5]
	global_load_dwordx4 v[120:123], v[120:121], off nt
	v_add_u32_e32 v4, v3, v25
	v_add_u32_e32 v125, v3, v35
	v_add_u32_e32 v126, 0x410, v4
	v_add_u32_e32 v127, 0x418, v4
	v_add_u32_e32 v128, 0x820, v4
	v_add_u32_e32 v129, 0x828, v4
	v_add_u32_e32 v130, 0xc30, v4
	v_add_u32_e32 v131, 0xc38, v4
	v_add_u32_e32 v132, 0x1040, v4
	v_add_u32_e32 v133, 0x1048, v4
	v_add_u32_e32 v134, 0x1450, v4
	s_waitcnt vmcnt(15)
	ds_write2_b32 v4, v60, v61 offset1:1
	ds_write2_b32 v4, v62, v63 offset0:2 offset1:3
	s_waitcnt vmcnt(14)
	ds_write2_b32 v126, v64, v65 offset1:1
	ds_write2_b32 v127, v66, v67 offset1:1
	s_waitcnt vmcnt(13)
	ds_write2_b32 v128, v68, v69 offset1:1
	ds_write2_b32 v129, v70, v71 offset1:1
	s_waitcnt vmcnt(12)
	ds_write2_b32 v130, v72, v73 offset1:1
	ds_write2_b32 v131, v74, v75 offset1:1
	s_waitcnt vmcnt(11)
	ds_write2_b32 v132, v76, v77 offset1:1
	ds_write2_b32 v133, v78, v79 offset1:1
	s_waitcnt vmcnt(10)
	ds_write2_b32 v134, v80, v81 offset1:1
	ds_write2_b32 v125, v82, v83 offset0:2 offset1:3
	v_add_u32_e32 v4, 0x410, v125
	s_waitcnt vmcnt(9)
	ds_write2_b32 v4, v84, v85 offset1:1
	v_add_u32_e32 v4, 0x418, v125
	ds_write2_b32 v4, v86, v87 offset1:1
	v_add_u32_e32 v4, 0x820, v125
	s_waitcnt vmcnt(8)
	ds_write2_b32 v4, v88, v89 offset1:1
	v_add_u32_e32 v4, 0x828, v125
	ds_write2_b32 v4, v90, v91 offset1:1
	v_add_u32_e32 v4, 0xc30, v125
	s_waitcnt vmcnt(7)
	ds_write2_b32 v4, v92, v93 offset1:1
	v_add_u32_e32 v4, 0xc38, v125
	ds_write2_b32 v4, v94, v95 offset1:1
	v_add_u32_e32 v4, 0x1040, v125
	s_waitcnt vmcnt(6)
	ds_write2_b32 v4, v96, v97 offset1:1
	v_add_u32_e32 v4, 0x1048, v125
	ds_write2_b32 v4, v98, v99 offset1:1
	v_add_u32_e32 v4, 0x1450, v125
	s_waitcnt vmcnt(5)
	ds_write2_b32 v4, v100, v101 offset1:1
	v_add_u32_e32 v4, v3, v41
	v_add_u32_e32 v60, 0x410, v4
	ds_write2_b32 v4, v102, v103 offset0:2 offset1:3
	s_waitcnt vmcnt(4)
	ds_write2_b32 v60, v104, v105 offset1:1
	v_add_u32_e32 v60, 0x418, v4
	ds_write2_b32 v60, v106, v107 offset1:1
	v_add_u32_e32 v60, 0x820, v4
	s_waitcnt vmcnt(3)
	ds_write2_b32 v60, v108, v109 offset1:1
	v_add_u32_e32 v60, 0x828, v4
	ds_write2_b32 v60, v110, v111 offset1:1
	v_add_u32_e32 v60, 0xc30, v4
	s_waitcnt vmcnt(2)
	ds_write2_b32 v60, v112, v113 offset1:1
	v_add_u32_e32 v60, 0xc38, v4
	ds_write2_b32 v60, v114, v115 offset1:1
	v_add_u32_e32 v60, 0x1040, v4
	s_waitcnt vmcnt(1)
; __device__ __forceinline__ unsigned cvt_pk_bf16(float lo, float hi) { unsigned r; asm("v_cvt_pk_bf16_f32 %0, %1, %2" : "=v"(r) : "v"(lo), "v"(hi)); return r; }
; __device__ __forceinline__ void convT_tile(const float* __restrict__ W, int K, int N, bf16_t* __restrict__ WT, int tile, unsigned char* shm, int wave, int lane) {
;     ...
;           T[rr * 65 + c4] = v.x; T[rr * 65 + c4 + 1] = v.y; T[rr * 65 + c4 + 2] = v.z; T[rr * 65 + c4 + 3] = v.w; } }
;     __builtin_amdgcn_fence(__ATOMIC_RELEASE, "wavefront"); __builtin_amdgcn_wave_barrier(); __builtin_amdgcn_fence(__ATOMIC_ACQUIRE, "wavefront");
;     { const int n8 = lane >> 3, k8 = (lane & 7) * 8;
; #pragma unroll
;       for (int i = 0; i < 8; ++i) { const int n = 8 * i + n8; const float* sp = T + k8 * 65 + n;
;           u32x4 o; o.x = cvt_pk_bf16(sp[0], sp[65]); o.y = cvt_pk_bf16(sp[2 * 65], sp[3 * 65]); o.z = cvt_pk_bf16(sp[4 * 65], sp[5 * 65]); o.w = cvt_pk_bf16(sp[6 * 65], sp[7 * 65]);
;           *(u32x4*)(WT + (size_t)(n0 + n) * K + k0 + k8) = o; } }
;     __builtin_amdgcn_fence(__ATOMIC_RELEASE, "wavefront"); __builtin_amdgcn_wave_barrier(); __builtin_amdgcn_fence(__ATOMIC_ACQUIRE, "wavefront");
	ds_write2_b32 v60, v116, v117 offset1:1
	v_add_u32_e32 v60, 0x1048, v4
	ds_write2_b32 v60, v118, v119 offset1:1
	v_add_u32_e32 v60, 0x1450, v4
	v_add_u32_e32 v4, 0x1458, v4
	s_waitcnt vmcnt(0)
	ds_write2_b32 v4, v122, v123 offset1:1
	v_lshlrev_b32_e32 v4, 1, v59
	v_add_u32_e32 v59, 0x400, v48
	v_lshl_add_u64 v[80:81], v[14:15], 0, v[4:5]
	v_or_b32_e32 v4, v124, v47
	ds_write2_b32 v60, v120, v121 offset1:1
	ds_read2_b32 v[64:65], v48 offset0:65 offset1:73
	ds_read2_b32 v[66:67], v48 offset1:8
	ds_read2_b32 v[68:69], v48 offset0:130 offset1:138
	ds_read2_b32 v[70:71], v48 offset0:195 offset1:203
	ds_read2_b32 v[72:73], v59 offset0:4 offset1:12
	ds_read2_b32 v[74:75], v59 offset0:69 offset1:77
	ds_read2_b32 v[76:77], v59 offset0:134 offset1:142
	ds_read2_b32 v[78:79], v59 offset0:199 offset1:207
	v_mul_u32_u24_e32 v4, 0x1600, v4
	v_lshlrev_b32_e32 v4, 1, v4
	v_lshl_add_u64 v[82:83], v[80:81], 0, v[4:5]
	v_or_b32_e32 v4, v124, v49
	v_mul_u32_u24_e32 v4, 0x1600, v4
	s_waitcnt lgkmcnt(6)
	v_cvt_pk_bf16_f32 v60, v66, v64
	v_lshlrev_b32_e32 v4, 1, v4
	s_waitcnt lgkmcnt(4)
	v_cvt_pk_bf16_f32 v61, v68, v70
	s_waitcnt lgkmcnt(2)
	v_cvt_pk_bf16_f32 v62, v72, v74
	s_waitcnt lgkmcnt(0)
	v_cvt_pk_bf16_f32 v63, v76, v78
	global_store_dwordx4 v[82:83], v[60:63], off
	s_nop 1
	v_cvt_pk_bf16_f32 v60, v67, v65
	v_lshl_add_u64 v[64:65], v[80:81], 0, v[4:5]
	v_or_b32_e32 v4, v124, v50
	v_cvt_pk_bf16_f32 v61, v69, v71
	v_cvt_pk_bf16_f32 v62, v73, v75
	v_cvt_pk_bf16_f32 v63, v77, v79
	ds_read2_b32 v[66:67], v48 offset0:16 offset1:24
	ds_read2_b32 v[68:69], v48 offset0:81 offset1:89
	ds_read2_b32 v[70:71], v48 offset0:146 offset1:154
	ds_read2_b32 v[72:73], v48 offset0:211 offset1:219
	ds_read2_b32 v[74:75], v59 offset0:20 offset1:28
	ds_read2_b32 v[76:77], v59 offset0:85 offset1:93
	ds_read2_b32 v[78:79], v59 offset0:150 offset1:158
	ds_read2_b32 v[82:83], v59 offset0:215 offset1:223
	v_mul_u32_u24_e32 v4, 0x1600, v4
	v_lshlrev_b32_e32 v4, 1, v4
	global_store_dwordx4 v[64:65], v[60:63], off
	v_lshl_add_u64 v[64:65], v[80:81], 0, v[4:5]
	v_or_b32_e32 v4, v124, v51
	v_mul_u32_u24_e32 v4, 0x1600, v4
	v_lshlrev_b32_e32 v4, 1, v4
	s_waitcnt lgkmcnt(6)
	v_cvt_pk_bf16_f32 v60, v66, v68
	s_waitcnt lgkmcnt(4)
	v_cvt_pk_bf16_f32 v61, v70, v72
	s_waitcnt lgkmcnt(2)
	v_cvt_pk_bf16_f32 v62, v74, v76
	s_waitcnt lgkmcnt(0)
	v_cvt_pk_bf16_f32 v63, v78, v82
	global_store_dwordx4 v[64:65], v[60:63], off
	v_lshl_add_u64 v[64:65], v[80:81], 0, v[4:5]
	v_or_b32_e32 v4, v124, v52
	v_cvt_pk_bf16_f32 v60, v67, v69
	v_cvt_pk_bf16_f32 v61, v71, v73
	v_cvt_pk_bf16_f32 v62, v75, v77
	v_cvt_pk_bf16_f32 v63, v79, v83
	ds_read2_b32 v[66:67], v48 offset0:32 offset1:40
	ds_read2_b32 v[68:69], v48 offset0:97 offset1:105
	ds_read2_b32 v[70:71], v48 offset0:162 offset1:170
	ds_read2_b32 v[72:73], v48 offset0:227 offset1:235
	ds_read2_b32 v[74:75], v59 offset0:36 offset1:44
	ds_read2_b32 v[76:77], v59 offset0:101 offset1:109
	ds_read2_b32 v[78:79], v59 offset0:166 offset1:174
	ds_read2_b32 v[82:83], v59 offset0:231 offset1:239
	v_mul_u32_u24_e32 v4, 0x1600, v4
	v_lshlrev_b32_e32 v4, 1, v4
	global_store_dwordx4 v[64:65], v[60:63], off
	v_lshl_add_u64 v[64:65], v[80:81], 0, v[4:5]
	v_or_b32_e32 v4, v124, v53
	v_mul_u32_u24_e32 v4, 0x1600, v4
	v_lshlrev_b32_e32 v4, 1, v4
	s_waitcnt lgkmcnt(6)
	v_cvt_pk_bf16_f32 v60, v66, v68
	s_waitcnt lgkmcnt(4)
	v_cvt_pk_bf16_f32 v61, v70, v72
	s_waitcnt lgkmcnt(2)
	v_cvt_pk_bf16_f32 v62, v74, v76
	s_waitcnt lgkmcnt(0)
	v_cvt_pk_bf16_f32 v63, v78, v82
	global_store_dwordx4 v[64:65], v[60:63], off
	v_lshl_add_u64 v[64:65], v[80:81], 0, v[4:5]
	v_or_b32_e32 v4, v124, v54
	v_cvt_pk_bf16_f32 v60, v67, v69
	v_cvt_pk_bf16_f32 v61, v71, v73
	v_cvt_pk_bf16_f32 v62, v75, v77
	v_cvt_pk_bf16_f32 v63, v79, v83
	ds_read2_b32 v[66:67], v48 offset0:48 offset1:56
	ds_read2_b32 v[68:69], v48 offset0:113 offset1:121
	ds_read2_b32 v[70:71], v48 offset0:178 offset1:186
	ds_read2_b32 v[72:73], v48 offset0:243 offset1:251
	ds_read2_b32 v[74:75], v59 offset0:52 offset1:60
	ds_read2_b32 v[76:77], v59 offset0:117 offset1:125
	ds_read2_b32 v[78:79], v59 offset0:182 offset1:190
	ds_read2_b32 v[82:83], v59 offset0:247 offset1:255
	v_mul_u32_u24_e32 v4, 0x1600, v4
	v_lshlrev_b32_e32 v4, 1, v4
	global_store_dwordx4 v[64:65], v[60:63], off
	v_lshl_add_u64 v[64:65], v[80:81], 0, v[4:5]
	v_or_b32_e32 v4, v124, v55
	v_mul_u32_u24_e32 v4, 0x1600, v4
	v_lshlrev_b32_e32 v4, 1, v4
	s_waitcnt lgkmcnt(6)
	v_cvt_pk_bf16_f32 v60, v66, v68
	s_waitcnt lgkmcnt(4)
	v_cvt_pk_bf16_f32 v61, v70, v72
	s_waitcnt lgkmcnt(2)
	v_cvt_pk_bf16_f32 v62, v74, v76
	s_waitcnt lgkmcnt(0)
	v_cvt_pk_bf16_f32 v63, v78, v82
	global_store_dwordx4 v[64:65], v[60:63], off
	v_lshl_add_u64 v[64:65], v[80:81], 0, v[4:5]
	s_nop 0
	v_cvt_pk_bf16_f32 v60, v67, v69
	v_cvt_pk_bf16_f32 v61, v71, v73
	v_cvt_pk_bf16_f32 v62, v75, v77
	v_cvt_pk_bf16_f32 v63, v79, v83
	global_store_dwordx4 v[64:65], v[60:63], off

; __device__ __forceinline__ void convT_tile(const float* __restrict__ W, int K, int N, bf16_t* __restrict__ WT, int tile, unsigned char* shm, int wave, int lane) {
;     const int ntn = N / 64, k0 = (tile / ntn) * 64, n0 = (tile % ntn) * 64;
;     float* T = (float*)shm + wave * (64 * 65);
;     { const int r4 = lane >> 4, c4 = (lane & 15) * 4;
; #pragma unroll
;       for (int i = 0; i < 16; ++i) { const int rr = 4 * i + r4; const float4 v = *(const float4*)(W + (size_t)(k0 + rr) * N + n0 + c4);
;           T[rr * 65 + c4] = v.x; T[rr * 65 + c4 + 1] = v.y; T[rr * 65 + c4 + 2] = v.z; T[rr * 65 + c4 + 3] = v.w; } }
.LBB0_204:
	s_andn2_saveexec_b64 s[10:11], s[10:11]
	s_cbranch_execz .LBB0_206
	v_add_u16_e32 v4, 0xf200, v58
	v_mul_u32_u24_e32 v59, 0xba2f, v4
	v_lshrrev_b32_e32 v59, 23, v59
	v_lshlrev_b16_e32 v124, 6, v59
	v_mul_lo_u16_e32 v59, 0xb0, v59
	v_sub_u16_e32 v4, v4, v59
	v_lshlrev_b16_e32 v59, 6, v4
	v_lshlrev_b32_e32 v4, 2, v59
	v_lshl_add_u64 v[120:121], v[16:17], 0, v[4:5]
	v_or_b32_e32 v4, v1, v124
	v_mul_u32_u24_e32 v4, 0x2c00, v4
	v_lshlrev_b32_e32 v4, 2, v4
	v_lshl_add_u64 v[68:69], v[120:121], 0, v[4:5]
	v_or_b32_e32 v4, v27, v124
	v_mul_u32_u24_e32 v4, 0x2c00, v4
	v_lshlrev_b32_e32 v4, 2, v4
	v_lshl_add_u64 v[70:71], v[120:121], 0, v[4:5]
	v_or_b32_e32 v4, v31, v124
	v_mul_u32_u24_e32 v4, 0x2c00, v4
	v_lshlrev_b32_e32 v4, 2, v4
	v_lshl_add_u64 v[76:77], v[120:121], 0, v[4:5]
	v_or_b32_e32 v4, v32, v124
	v_mul_u32_u24_e32 v4, 0x2c00, v4
	v_lshlrev_b32_e32 v4, 2, v4
	v_lshl_add_u64 v[78:79], v[120:121], 0, v[4:5]
	v_or_b32_e32 v4, v33, v124
	v_mul_u32_u24_e32 v4, 0x2c00, v4
	v_lshlrev_b32_e32 v4, 2, v4
	v_lshl_add_u64 v[84:85], v[120:121], 0, v[4:5]
	v_or_b32_e32 v4, v34, v124
	v_mul_u32_u24_e32 v4, 0x2c00, v4
	v_lshlrev_b32_e32 v4, 2, v4
	v_lshl_add_u64 v[86:87], v[120:121], 0, v[4:5]
	v_or_b32_e32 v4, v36, v124
	v_mul_u32_u24_e32 v4, 0x2c00, v4
	v_lshlrev_b32_e32 v4, 2, v4
	v_lshl_add_u64 v[92:93], v[120:121], 0, v[4:5]
	v_or_b32_e32 v4, v37, v124
	v_mul_u32_u24_e32 v4, 0x2c00, v4
	global_load_dwordx4 v[60:63], v[68:69], off nt
	global_load_dwordx4 v[64:67], v[70:71], off nt
	v_lshlrev_b32_e32 v4, 2, v4
	v_lshl_add_u64 v[94:95], v[120:121], 0, v[4:5]
	v_or_b32_e32 v4, v38, v124
	v_mul_u32_u24_e32 v4, 0x2c00, v4
	global_load_dwordx4 v[68:71], v[76:77], off nt
	global_load_dwordx4 v[72:75], v[78:79], off nt
	v_lshlrev_b32_e32 v4, 2, v4
	v_lshl_add_u64 v[100:101], v[120:121], 0, v[4:5]
	v_or_b32_e32 v4, v39, v124
	v_mul_u32_u24_e32 v4, 0x2c00, v4
	v_lshlrev_b32_e32 v4, 2, v4
	global_load_dwordx4 v[76:79], v[84:85], off nt
	global_load_dwordx4 v[80:83], v[86:87], off nt
	v_lshl_add_u64 v[102:103], v[120:121], 0, v[4:5]
	v_or_b32_e32 v4, v40, v124
	v_mul_u32_u24_e32 v4, 0x2c00, v4
	v_lshlrev_b32_e32 v4, 2, v4
	global_load_dwordx4 v[84:87], v[92:93], off nt
	global_load_dwordx4 v[88:91], v[94:95], off nt
	v_lshl_add_u64 v[108:109], v[120:121], 0, v[4:5]
	v_or_b32_e32 v4, v42, v124
	v_mul_u32_u24_e32 v4, 0x2c00, v4
	v_lshlrev_b32_e32 v4, 2, v4
	v_lshl_add_u64 v[110:111], v[120:121], 0, v[4:5]
	v_or_b32_e32 v4, v43, v124
	global_load_dwordx4 v[92:95], v[100:101], off nt
	global_load_dwordx4 v[96:99], v[102:103], off nt
	v_mul_u32_u24_e32 v4, 0x2c00, v4
	v_lshlrev_b32_e32 v4, 2, v4
	global_load_dwordx4 v[100:103], v[108:109], off nt
	global_load_dwordx4 v[104:107], v[110:111], off nt
	v_lshl_add_u64 v[108:109], v[120:121], 0, v[4:5]
	v_or_b32_e32 v4, v44, v124
	v_mul_u32_u24_e32 v4, 0x2c00, v4
	v_lshlrev_b32_e32 v4, 2, v4
	v_lshl_add_u64 v[112:113], v[120:121], 0, v[4:5]
	v_or_b32_e32 v4, v45, v124
	global_load_dwordx4 v[108:111], v[108:109], off nt
	v_mul_u32_u24_e32 v4, 0x2c00, v4
	v_lshlrev_b32_e32 v4, 2, v4
	global_load_dwordx4 v[112:115], v[112:113], off nt
	v_lshl_add_u64 v[116:117], v[120:121], 0, v[4:5]
	v_or_b32_e32 v4, v46, v124
	v_mul_u32_u24_e32 v4, 0x2c00, v4
	global_load_dwordx4 v[116:119], v[116:117], off nt
	v_lshlrev_b32_e32 v4, 2, v4
	v_lshl_add_u64 v[120:121], v[120:121], 0, v[4:5]
	global_load_dwordx4 v[120:123], v[120:121], off nt
	v_add_u32_e32 v4, v3, v25
	s_waitcnt vmcnt(15)
	ds_write2_b32 v4, v60, v61 offset1:1
	ds_write2_b32 v4, v62, v63 offset0:2 offset1:3
	v_add_u32_e32 v60, 0x410, v4
	s_waitcnt vmcnt(14)
	ds_write2_b32 v60, v64, v65 offset1:1
	v_add_u32_e32 v60, 0x418, v4
	ds_write2_b32 v60, v66, v67 offset1:1
	v_add_u32_e32 v60, 0x820, v4
	s_waitcnt vmcnt(13)
	ds_write2_b32 v60, v68, v69 offset1:1
	v_add_u32_e32 v60, 0x828, v4
	ds_write2_b32 v60, v70, v71 offset1:1
	v_add_u32_e32 v60, 0xc30, v4
	s_waitcnt vmcnt(12)
	ds_write2_b32 v60, v72, v73 offset1:1
	v_add_u32_e32 v60, 0xc38, v4
	ds_write2_b32 v60, v74, v75 offset1:1
	v_add_u32_e32 v60, 0x1040, v4
	s_waitcnt vmcnt(11)
	ds_write2_b32 v60, v76, v77 offset1:1
	v_add_u32_e32 v60, 0x1048, v4
	v_add_u32_e32 v4, 0x1450, v4
	s_waitcnt vmcnt(10)
	ds_write2_b32 v4, v80, v81 offset1:1
	v_add_u32_e32 v4, v3, v35
	ds_write2_b32 v60, v78, v79 offset1:1
	v_add_u32_e32 v60, 0x410, v4
	s_waitcnt vmcnt(9)
	ds_write2_b32 v60, v84, v85 offset1:1
	v_add_u32_e32 v60, 0x418, v4
	ds_write2_b32 v60, v86, v87 offset1:1
	v_add_u32_e32 v60, 0x820, v4
	s_waitcnt vmcnt(8)
	ds_write2_b32 v60, v88, v89 offset1:1
	v_add_u32_e32 v60, 0x828, v4
	ds_write2_b32 v60, v90, v91 offset1:1
	v_add_u32_e32 v60, 0xc30, v4
	s_waitcnt vmcnt(7)
	ds_write2_b32 v60, v92, v93 offset1:1
	v_add_u32_e32 v60, 0xc38, v4
	ds_write2_b32 v60, v94, v95 offset1:1
	v_add_u32_e32 v60, 0x1040, v4
	ds_write2_b32 v4, v82, v83 offset0:2 offset1:3
	s_waitcnt vmcnt(6)
	ds_write2_b32 v60, v96, v97 offset1:1
	v_add_u32_e32 v60, 0x1048, v4
	v_add_u32_e32 v4, 0x1450, v4
	s_waitcnt vmcnt(5)
	ds_write2_b32 v4, v100, v101 offset1:1
	v_add_u32_e32 v4, v3, v41
	ds_write2_b32 v60, v98, v99 offset1:1
	v_add_u32_e32 v60, 0x410, v4
	s_waitcnt vmcnt(4)
; __device__ __forceinline__ unsigned cvt_pk_bf16(float lo, float hi) { unsigned r; asm("v_cvt_pk_bf16_f32 %0, %1, %2" : "=v"(r) : "v"(lo), "v"(hi)); return r; }
; __device__ __forceinline__ void convT_tile(const float* __restrict__ W, int K, int N, bf16_t* __restrict__ WT, int tile, unsigned char* shm, int wave, int lane) {
;     ...
;           T[rr * 65 + c4] = v.x; T[rr * 65 + c4 + 1] = v.y; T[rr * 65 + c4 + 2] = v.z; T[rr * 65 + c4 + 3] = v.w; } }
;     __builtin_amdgcn_fence(__ATOMIC_RELEASE, "wavefront"); __builtin_amdgcn_wave_barrier(); __builtin_amdgcn_fence(__ATOMIC_ACQUIRE, "wavefront");
;     { const int n8 = lane >> 3, k8 = (lane & 7) * 8;
; #pragma unroll
;       for (int i = 0; i < 8; ++i) { const int n = 8 * i + n8; const float* sp = T + k8 * 65 + n;
;           u32x4 o; o.x = cvt_pk_bf16(sp[0], sp[65]); o.y = cvt_pk_bf16(sp[2 * 65], sp[3 * 65]); o.z = cvt_pk_bf16(sp[4 * 65], sp[5 * 65]); o.w = cvt_pk_bf16(sp[6 * 65], sp[7 * 65]);
;           *(u32x4*)(WT + (size_t)(n0 + n) * K + k0 + k8) = o; } }
;     __builtin_amdgcn_fence(__ATOMIC_RELEASE, "wavefront"); __builtin_amdgcn_wave_barrier(); __builtin_amdgcn_fence(__ATOMIC_ACQUIRE, "wavefront");
	ds_write2_b32 v60, v104, v105 offset1:1
	v_add_u32_e32 v60, 0x418, v4
	ds_write2_b32 v60, v106, v107 offset1:1
	v_add_u32_e32 v60, 0x820, v4
	s_waitcnt vmcnt(3)
	ds_write2_b32 v60, v108, v109 offset1:1
	v_add_u32_e32 v60, 0x828, v4
	ds_write2_b32 v60, v110, v111 offset1:1
	v_add_u32_e32 v60, 0xc30, v4
	s_waitcnt vmcnt(2)
	ds_write2_b32 v60, v112, v113 offset1:1
	v_add_u32_e32 v60, 0xc38, v4
	ds_write2_b32 v60, v114, v115 offset1:1
	v_add_u32_e32 v60, 0x1040, v4
	s_waitcnt vmcnt(1)
	ds_write2_b32 v60, v116, v117 offset1:1
	v_add_u32_e32 v60, 0x1048, v4
	ds_write2_b32 v4, v102, v103 offset0:2 offset1:3
	ds_write2_b32 v60, v118, v119 offset1:1
	v_add_u32_e32 v60, 0x1450, v4
	v_add_u32_e32 v4, 0x1458, v4
	v_add_u32_e32 v84, 0x400, v48
	s_waitcnt vmcnt(0)
	ds_write2_b32 v60, v120, v121 offset1:1
	ds_write2_b32 v4, v122, v123 offset1:1
	ds_read2_b32 v[64:65], v48 offset0:65 offset1:73
	ds_read2_b32 v[66:67], v48 offset1:8
	ds_read2_b32 v[68:69], v48 offset0:130 offset1:138
	ds_read2_b32 v[70:71], v48 offset0:195 offset1:203
	ds_read2_b32 v[72:73], v84 offset0:4 offset1:12
	ds_read2_b32 v[74:75], v84 offset0:69 offset1:77
	ds_read2_b32 v[76:77], v84 offset0:134 offset1:142
	ds_read2_b32 v[78:79], v84 offset0:199 offset1:207
	v_lshlrev_b32_e32 v4, 1, v124
	v_lshl_add_u64 v[80:81], v[18:19], 0, v[4:5]
	v_or_b32_e32 v4, v47, v59
	v_lshlrev_b32_e32 v4, 12, v4
	v_lshl_add_u64 v[82:83], v[80:81], 0, v[4:5]
	s_waitcnt lgkmcnt(6)
	v_cvt_pk_bf16_f32 v60, v66, v64
	s_waitcnt lgkmcnt(4)
	v_cvt_pk_bf16_f32 v61, v68, v70
	s_waitcnt lgkmcnt(2)
	v_cvt_pk_bf16_f32 v62, v72, v74
	s_waitcnt lgkmcnt(0)
	v_cvt_pk_bf16_f32 v63, v76, v78
	global_store_dwordx4 v[82:83], v[60:63], off
	v_or_b32_e32 v4, v49, v59
	v_lshlrev_b32_e32 v4, 12, v4
	v_cvt_pk_bf16_f32 v60, v67, v65
	v_cvt_pk_bf16_f32 v61, v69, v71
	v_cvt_pk_bf16_f32 v62, v73, v75
	v_cvt_pk_bf16_f32 v63, v77, v79
	ds_read2_b32 v[66:67], v48 offset0:16 offset1:24
	ds_read2_b32 v[68:69], v48 offset0:81 offset1:89
	ds_read2_b32 v[70:71], v48 offset0:146 offset1:154
	ds_read2_b32 v[72:73], v48 offset0:211 offset1:219
	ds_read2_b32 v[74:75], v84 offset0:20 offset1:28
	ds_read2_b32 v[76:77], v84 offset0:85 offset1:93
	ds_read2_b32 v[78:79], v84 offset0:150 offset1:158
	ds_read2_b32 v[82:83], v84 offset0:215 offset1:223
	v_lshl_add_u64 v[64:65], v[80:81], 0, v[4:5]
	v_or_b32_e32 v4, v50, v59
	v_lshlrev_b32_e32 v4, 12, v4
	global_store_dwordx4 v[64:65], v[60:63], off
	v_lshl_add_u64 v[64:65], v[80:81], 0, v[4:5]
	v_or_b32_e32 v4, v51, v59
	s_waitcnt lgkmcnt(6)
	v_cvt_pk_bf16_f32 v60, v66, v68
	s_waitcnt lgkmcnt(4)
	v_cvt_pk_bf16_f32 v61, v70, v72
	s_waitcnt lgkmcnt(2)
	v_cvt_pk_bf16_f32 v62, v74, v76
	s_waitcnt lgkmcnt(0)
	v_cvt_pk_bf16_f32 v63, v78, v82
	global_store_dwordx4 v[64:65], v[60:63], off
	v_lshlrev_b32_e32 v4, 12, v4
	v_lshl_add_u64 v[64:65], v[80:81], 0, v[4:5]
	v_cvt_pk_bf16_f32 v60, v67, v69
	v_cvt_pk_bf16_f32 v61, v71, v73
	v_cvt_pk_bf16_f32 v62, v75, v77
	v_cvt_pk_bf16_f32 v63, v79, v83
	ds_read2_b32 v[66:67], v48 offset0:32 offset1:40
	ds_read2_b32 v[68:69], v48 offset0:97 offset1:105
	ds_read2_b32 v[70:71], v48 offset0:162 offset1:170
	ds_read2_b32 v[72:73], v48 offset0:227 offset1:235
	ds_read2_b32 v[74:75], v84 offset0:36 offset1:44
	ds_read2_b32 v[76:77], v84 offset0:101 offset1:109
	ds_read2_b32 v[78:79], v84 offset0:166 offset1:174
	ds_read2_b32 v[82:83], v84 offset0:231 offset1:239
	v_or_b32_e32 v4, v52, v59
	v_lshlrev_b32_e32 v4, 12, v4
	global_store_dwordx4 v[64:65], v[60:63], off
	v_lshl_add_u64 v[64:65], v[80:81], 0, v[4:5]
	v_or_b32_e32 v4, v53, v59
	s_waitcnt lgkmcnt(6)
	v_cvt_pk_bf16_f32 v60, v66, v68
	s_waitcnt lgkmcnt(4)
	v_cvt_pk_bf16_f32 v61, v70, v72
	s_waitcnt lgkmcnt(2)
	v_cvt_pk_bf16_f32 v62, v74, v76
	s_waitcnt lgkmcnt(0)
	v_cvt_pk_bf16_f32 v63, v78, v82
	global_store_dwordx4 v[64:65], v[60:63], off
	v_lshlrev_b32_e32 v4, 12, v4
	v_lshl_add_u64 v[64:65], v[80:81], 0, v[4:5]
	v_cvt_pk_bf16_f32 v60, v67, v69
	v_cvt_pk_bf16_f32 v61, v71, v73
	v_cvt_pk_bf16_f32 v62, v75, v77
	v_cvt_pk_bf16_f32 v63, v79, v83
	ds_read2_b32 v[66:67], v48 offset0:48 offset1:56
	ds_read2_b32 v[68:69], v48 offset0:113 offset1:121
	ds_read2_b32 v[70:71], v48 offset0:178 offset1:186
	ds_read2_b32 v[72:73], v48 offset0:243 offset1:251
	ds_read2_b32 v[74:75], v84 offset0:52 offset1:60
	ds_read2_b32 v[76:77], v84 offset0:117 offset1:125
	ds_read2_b32 v[78:79], v84 offset0:182 offset1:190
	ds_read2_b32 v[82:83], v84 offset0:247 offset1:255
	v_or_b32_e32 v4, v54, v59
	v_lshlrev_b32_e32 v4, 12, v4
	global_store_dwordx4 v[64:65], v[60:63], off
	v_lshl_add_u64 v[64:65], v[80:81], 0, v[4:5]
	v_or_b32_e32 v4, v55, v59
	v_lshlrev_b32_e32 v4, 12, v4
	s_waitcnt lgkmcnt(6)
	v_cvt_pk_bf16_f32 v60, v66, v68
	s_waitcnt lgkmcnt(4)
	v_cvt_pk_bf16_f32 v61, v70, v72
	s_waitcnt lgkmcnt(2)
	v_cvt_pk_bf16_f32 v62, v74, v76
	s_waitcnt lgkmcnt(0)
	v_cvt_pk_bf16_f32 v63, v78, v82
	global_store_dwordx4 v[64:65], v[60:63], off
	v_lshl_add_u64 v[64:65], v[80:81], 0, v[4:5]
	s_nop 0
	v_cvt_pk_bf16_f32 v60, v67, v69
	v_cvt_pk_bf16_f32 v61, v71, v73
	v_cvt_pk_bf16_f32 v62, v75, v77
	v_cvt_pk_bf16_f32 v63, v79, v83
	global_store_dwordx4 v[64:65], v[60:63], off

; __device__ __forceinline__ void convT_tile(const float* __restrict__ W, int K, int N, bf16_t* __restrict__ WT, int tile, unsigned char* shm, int wave, int lane) {
;     const int ntn = N / 64, k0 = (tile / ntn) * 64, n0 = (tile % ntn) * 64;
;     float* T = (float*)shm + wave * (64 * 65);
;     { const int r4 = lane >> 4, c4 = (lane & 15) * 4;
; #pragma unroll
;       for (int i = 0; i < 16; ++i) { const int rr = 4 * i + r4; const float4 v = *(const float4*)(W + (size_t)(k0 + rr) * N + n0 + c4);
;           T[rr * 65 + c4] = v.x; T[rr * 65 + c4 + 1] = v.y; T[rr * 65 + c4 + 2] = v.z; T[rr * 65 + c4 + 3] = v.w; } }
; __device__ __forceinline__ void phase_lprep(PRef p, int layer, unsigned char* shm, const float* hL_, const float* hC_) {
;     ...
;         if (r < T_UP) { convT_tile(p.in[30] + (size_t)layer * 2048 * 11264, 2048, 11264, (bf16_t*)(p.ws + O_WT_UP), r, shm, wave, lane); continue; } r -= T_UP;
.LBB0_207:
	s_andn2_saveexec_b64 s[8:9], s[8:9]
	s_cbranch_execz .LBB0_209
	v_add_u32_e32 v4, 0x3400, v57
	v_and_b32_e32 v124, 0x7c0, v30
	v_and_b32_e32 v59, 0x1ffc0, v4
	v_lshlrev_b32_e32 v4, 2, v124
	v_lshl_add_u64 v[120:121], v[20:21], 0, v[4:5]
	v_or_b32_e32 v4, v59, v1
	v_lshlrev_b32_e32 v4, 13, v4
	v_lshl_add_u64 v[68:69], v[120:121], 0, v[4:5]
	v_or_b32_e32 v4, v59, v27
	v_lshlrev_b32_e32 v4, 13, v4
	v_lshl_add_u64 v[70:71], v[120:121], 0, v[4:5]
	v_or_b32_e32 v4, v59, v31
	v_lshlrev_b32_e32 v4, 13, v4
	v_lshl_add_u64 v[76:77], v[120:121], 0, v[4:5]
	v_or_b32_e32 v4, v59, v32
	v_lshlrev_b32_e32 v4, 13, v4
	v_lshl_add_u64 v[78:79], v[120:121], 0, v[4:5]
	v_or_b32_e32 v4, v59, v33
	v_lshlrev_b32_e32 v4, 13, v4
	v_lshl_add_u64 v[84:85], v[120:121], 0, v[4:5]
	v_or_b32_e32 v4, v59, v34
	v_lshlrev_b32_e32 v4, 13, v4
	v_lshl_add_u64 v[86:87], v[120:121], 0, v[4:5]
	v_or_b32_e32 v4, v59, v36
	v_lshlrev_b32_e32 v4, 13, v4
	global_load_dwordx4 v[60:63], v[68:69], off nt
	global_load_dwordx4 v[64:67], v[70:71], off nt
	s_nop 0
	global_load_dwordx4 v[68:71], v[76:77], off nt
	global_load_dwordx4 v[72:75], v[78:79], off nt
	s_nop 0
	global_load_dwordx4 v[76:79], v[84:85], off nt
	global_load_dwordx4 v[80:83], v[86:87], off nt
	v_lshl_add_u64 v[84:85], v[120:121], 0, v[4:5]
	v_or_b32_e32 v4, v59, v37
	global_load_dwordx4 v[84:87], v[84:85], off nt
	v_lshlrev_b32_e32 v4, 13, v4
	v_lshl_add_u64 v[88:89], v[120:121], 0, v[4:5]
	v_or_b32_e32 v4, v59, v38
	global_load_dwordx4 v[88:91], v[88:89], off nt
	v_lshlrev_b32_e32 v4, 13, v4
	v_lshl_add_u64 v[92:93], v[120:121], 0, v[4:5]
	v_or_b32_e32 v4, v59, v39
	global_load_dwordx4 v[92:95], v[92:93], off nt
	v_lshlrev_b32_e32 v4, 13, v4
	v_lshl_add_u64 v[96:97], v[120:121], 0, v[4:5]
	v_or_b32_e32 v4, v59, v40
	global_load_dwordx4 v[96:99], v[96:97], off nt
	v_lshlrev_b32_e32 v4, 13, v4
	v_lshl_add_u64 v[100:101], v[120:121], 0, v[4:5]
	v_or_b32_e32 v4, v59, v42
	global_load_dwordx4 v[100:103], v[100:101], off nt
	v_lshlrev_b32_e32 v4, 13, v4
	v_lshl_add_u64 v[104:105], v[120:121], 0, v[4:5]
	v_or_b32_e32 v4, v59, v43
	global_load_dwordx4 v[104:107], v[104:105], off nt
	v_lshlrev_b32_e32 v4, 13, v4
	v_lshl_add_u64 v[108:109], v[120:121], 0, v[4:5]
	v_or_b32_e32 v4, v59, v44
	global_load_dwordx4 v[108:111], v[108:109], off nt
	v_lshlrev_b32_e32 v4, 13, v4
	v_lshl_add_u64 v[112:113], v[120:121], 0, v[4:5]
	v_or_b32_e32 v4, v59, v45
	global_load_dwordx4 v[112:115], v[112:113], off nt
	v_lshlrev_b32_e32 v4, 13, v4
	v_lshl_add_u64 v[116:117], v[120:121], 0, v[4:5]
	v_or_b32_e32 v4, v59, v46
	global_load_dwordx4 v[116:119], v[116:117], off nt
	v_lshlrev_b32_e32 v4, 13, v4
	v_lshl_add_u64 v[120:121], v[120:121], 0, v[4:5]
	global_load_dwordx4 v[120:123], v[120:121], off nt
	v_add_u32_e32 v4, v3, v25
	v_add_u32_e32 v125, v3, v35
	v_add_u32_e32 v126, 0x410, v4
	v_add_u32_e32 v127, 0x418, v4
	v_add_u32_e32 v128, 0x820, v4
	v_add_u32_e32 v129, 0x828, v4
	v_add_u32_e32 v130, 0xc30, v4
	v_add_u32_e32 v131, 0xc38, v4
	v_add_u32_e32 v132, 0x1040, v4
	v_add_u32_e32 v133, 0x1048, v4
	v_add_u32_e32 v134, 0x1450, v4
	s_waitcnt vmcnt(15)
	ds_write2_b32 v4, v60, v61 offset1:1
	ds_write2_b32 v4, v62, v63 offset0:2 offset1:3
	s_waitcnt vmcnt(14)
	ds_write2_b32 v126, v64, v65 offset1:1
	ds_write2_b32 v127, v66, v67 offset1:1
	s_waitcnt vmcnt(13)
	ds_write2_b32 v128, v68, v69 offset1:1
	ds_write2_b32 v129, v70, v71 offset1:1
	s_waitcnt vmcnt(12)
	ds_write2_b32 v130, v72, v73 offset1:1
	ds_write2_b32 v131, v74, v75 offset1:1
	s_waitcnt vmcnt(11)
	ds_write2_b32 v132, v76, v77 offset1:1
	ds_write2_b32 v133, v78, v79 offset1:1
	s_waitcnt vmcnt(10)
	ds_write2_b32 v134, v80, v81 offset1:1
	ds_write2_b32 v125, v82, v83 offset0:2 offset1:3
	v_add_u32_e32 v4, 0x410, v125
	s_waitcnt vmcnt(9)
	ds_write2_b32 v4, v84, v85 offset1:1
	v_add_u32_e32 v4, 0x418, v125
	ds_write2_b32 v4, v86, v87 offset1:1
	v_add_u32_e32 v4, 0x820, v125
	s_waitcnt vmcnt(8)
	ds_write2_b32 v4, v88, v89 offset1:1
	v_add_u32_e32 v4, 0x828, v125
	ds_write2_b32 v4, v90, v91 offset1:1
	v_add_u32_e32 v4, 0xc30, v125
	s_waitcnt vmcnt(7)
	ds_write2_b32 v4, v92, v93 offset1:1
	v_add_u32_e32 v4, 0xc38, v125
	ds_write2_b32 v4, v94, v95 offset1:1
	v_add_u32_e32 v4, 0x1040, v125
	s_waitcnt vmcnt(6)
	ds_write2_b32 v4, v96, v97 offset1:1
	v_add_u32_e32 v4, 0x1048, v125
	ds_write2_b32 v4, v98, v99 offset1:1
	v_add_u32_e32 v4, 0x1450, v125
	s_waitcnt vmcnt(5)
	ds_write2_b32 v4, v100, v101 offset1:1
	v_add_u32_e32 v4, v3, v41
	v_add_u32_e32 v60, 0x410, v4
	ds_write2_b32 v4, v102, v103 offset0:2 offset1:3
	s_waitcnt vmcnt(4)
	ds_write2_b32 v60, v104, v105 offset1:1
	v_add_u32_e32 v60, 0x418, v4
	ds_write2_b32 v60, v106, v107 offset1:1
	v_add_u32_e32 v60, 0x820, v4
	s_waitcnt vmcnt(3)
	ds_write2_b32 v60, v108, v109 offset1:1
	v_add_u32_e32 v60, 0x828, v4
	ds_write2_b32 v60, v110, v111 offset1:1
	v_add_u32_e32 v60, 0xc30, v4
	s_waitcnt vmcnt(2)
; __device__ __forceinline__ unsigned cvt_pk_bf16(float lo, float hi) { unsigned r; asm("v_cvt_pk_bf16_f32 %0, %1, %2" : "=v"(r) : "v"(lo), "v"(hi)); return r; }
; __device__ __forceinline__ void convT_tile(const float* __restrict__ W, int K, int N, bf16_t* __restrict__ WT, int tile, unsigned char* shm, int wave, int lane) {
;     ...
;     __builtin_amdgcn_fence(__ATOMIC_RELEASE, "wavefront"); __builtin_amdgcn_wave_barrier(); __builtin_amdgcn_fence(__ATOMIC_ACQUIRE, "wavefront");
;     { const int n8 = lane >> 3, k8 = (lane & 7) * 8;
; #pragma unroll
;       for (int i = 0; i < 8; ++i) { const int n = 8 * i + n8; const float* sp = T + k8 * 65 + n;
;           u32x4 o; o.x = cvt_pk_bf16(sp[0], sp[65]); o.y = cvt_pk_bf16(sp[2 * 65], sp[3 * 65]); o.z = cvt_pk_bf16(sp[4 * 65], sp[5 * 65]); o.w = cvt_pk_bf16(sp[6 * 65], sp[7 * 65]);
;           *(u32x4*)(WT + (size_t)(n0 + n) * K + k0 + k8) = o; } }
;     __builtin_amdgcn_fence(__ATOMIC_RELEASE, "wavefront"); __builtin_amdgcn_wave_barrier(); __builtin_amdgcn_fence(__ATOMIC_ACQUIRE, "wavefront");
	ds_write2_b32 v60, v112, v113 offset1:1
	v_add_u32_e32 v60, 0xc38, v4
	ds_write2_b32 v60, v114, v115 offset1:1
	v_add_u32_e32 v60, 0x1040, v4
	s_waitcnt vmcnt(1)
	ds_write2_b32 v60, v116, v117 offset1:1
	v_add_u32_e32 v60, 0x1048, v4
	ds_write2_b32 v60, v118, v119 offset1:1
	v_add_u32_e32 v60, 0x1450, v4
	v_add_u32_e32 v4, 0x1458, v4
	s_waitcnt vmcnt(0)
	ds_write2_b32 v4, v122, v123 offset1:1
	v_lshlrev_b32_e32 v4, 1, v59
	v_add_u32_e32 v59, 0x400, v48
	ds_write2_b32 v60, v120, v121 offset1:1
	ds_read2_b32 v[64:65], v48 offset0:65 offset1:73
	ds_read2_b32 v[66:67], v48 offset1:8
	ds_read2_b32 v[68:69], v48 offset0:130 offset1:138
	ds_read2_b32 v[70:71], v48 offset0:195 offset1:203
	ds_read2_b32 v[72:73], v59 offset0:4 offset1:12
	ds_read2_b32 v[74:75], v59 offset0:69 offset1:77
	ds_read2_b32 v[76:77], v59 offset0:134 offset1:142
	ds_read2_b32 v[78:79], v59 offset0:199 offset1:207
	v_lshl_add_u64 v[80:81], v[22:23], 0, v[4:5]
	v_or_b32_e32 v4, v124, v47
	v_lshlrev_b32_e32 v4, 12, v4
	v_lshl_add_u64 v[82:83], v[80:81], 0, v[4:5]
	s_waitcnt lgkmcnt(6)
	v_cvt_pk_bf16_f32 v60, v66, v64
	s_waitcnt lgkmcnt(4)
	v_cvt_pk_bf16_f32 v61, v68, v70
	s_waitcnt lgkmcnt(2)
	v_cvt_pk_bf16_f32 v62, v72, v74
	s_waitcnt lgkmcnt(0)
	v_cvt_pk_bf16_f32 v63, v76, v78
	global_store_dwordx4 v[82:83], v[60:63], off
	v_or_b32_e32 v4, v124, v49
	v_lshlrev_b32_e32 v4, 12, v4
	v_cvt_pk_bf16_f32 v60, v67, v65
	v_cvt_pk_bf16_f32 v61, v69, v71
	v_cvt_pk_bf16_f32 v62, v73, v75
	v_cvt_pk_bf16_f32 v63, v77, v79
	ds_read2_b32 v[66:67], v48 offset0:16 offset1:24
	ds_read2_b32 v[68:69], v48 offset0:81 offset1:89
	ds_read2_b32 v[70:71], v48 offset0:146 offset1:154
	ds_read2_b32 v[72:73], v48 offset0:211 offset1:219
	ds_read2_b32 v[74:75], v59 offset0:20 offset1:28
	ds_read2_b32 v[76:77], v59 offset0:85 offset1:93
	ds_read2_b32 v[78:79], v59 offset0:150 offset1:158
	ds_read2_b32 v[82:83], v59 offset0:215 offset1:223
	v_lshl_add_u64 v[64:65], v[80:81], 0, v[4:5]
	v_or_b32_e32 v4, v124, v50
	v_lshlrev_b32_e32 v4, 12, v4
	global_store_dwordx4 v[64:65], v[60:63], off
	v_lshl_add_u64 v[64:65], v[80:81], 0, v[4:5]
	v_or_b32_e32 v4, v124, v51
	s_waitcnt lgkmcnt(6)
	v_cvt_pk_bf16_f32 v60, v66, v68
	s_waitcnt lgkmcnt(4)
	v_cvt_pk_bf16_f32 v61, v70, v72
	s_waitcnt lgkmcnt(2)
	v_cvt_pk_bf16_f32 v62, v74, v76
	s_waitcnt lgkmcnt(0)
	v_cvt_pk_bf16_f32 v63, v78, v82
	global_store_dwordx4 v[64:65], v[60:63], off
	v_lshlrev_b32_e32 v4, 12, v4
	v_lshl_add_u64 v[64:65], v[80:81], 0, v[4:5]
	v_cvt_pk_bf16_f32 v60, v67, v69
	v_cvt_pk_bf16_f32 v61, v71, v73
	v_cvt_pk_bf16_f32 v62, v75, v77
	v_cvt_pk_bf16_f32 v63, v79, v83
	ds_read2_b32 v[66:67], v48 offset0:32 offset1:40
	ds_read2_b32 v[68:69], v48 offset0:97 offset1:105
	ds_read2_b32 v[70:71], v48 offset0:162 offset1:170
	ds_read2_b32 v[72:73], v48 offset0:227 offset1:235
	ds_read2_b32 v[74:75], v59 offset0:36 offset1:44
	ds_read2_b32 v[76:77], v59 offset0:101 offset1:109
	ds_read2_b32 v[78:79], v59 offset0:166 offset1:174
	ds_read2_b32 v[82:83], v59 offset0:231 offset1:239
	v_or_b32_e32 v4, v124, v52
	v_lshlrev_b32_e32 v4, 12, v4
	global_store_dwordx4 v[64:65], v[60:63], off
	v_lshl_add_u64 v[64:65], v[80:81], 0, v[4:5]
	v_or_b32_e32 v4, v124, v53
	s_waitcnt lgkmcnt(6)
	v_cvt_pk_bf16_f32 v60, v66, v68
	s_waitcnt lgkmcnt(4)
	v_cvt_pk_bf16_f32 v61, v70, v72
	s_waitcnt lgkmcnt(2)
	v_cvt_pk_bf16_f32 v62, v74, v76
	s_waitcnt lgkmcnt(0)
	v_cvt_pk_bf16_f32 v63, v78, v82
	global_store_dwordx4 v[64:65], v[60:63], off
	v_lshlrev_b32_e32 v4, 12, v4
	v_lshl_add_u64 v[64:65], v[80:81], 0, v[4:5]
	v_cvt_pk_bf16_f32 v60, v67, v69
	v_cvt_pk_bf16_f32 v61, v71, v73
	v_cvt_pk_bf16_f32 v62, v75, v77
	v_cvt_pk_bf16_f32 v63, v79, v83
	ds_read2_b32 v[66:67], v48 offset0:48 offset1:56
	ds_read2_b32 v[68:69], v48 offset0:113 offset1:121
	ds_read2_b32 v[70:71], v48 offset0:178 offset1:186
	ds_read2_b32 v[72:73], v48 offset0:243 offset1:251
	ds_read2_b32 v[74:75], v59 offset0:52 offset1:60
	ds_read2_b32 v[76:77], v59 offset0:117 offset1:125
	ds_read2_b32 v[78:79], v59 offset0:182 offset1:190
	ds_read2_b32 v[82:83], v59 offset0:247 offset1:255
	v_or_b32_e32 v4, v124, v54
	v_lshlrev_b32_e32 v4, 12, v4
	global_store_dwordx4 v[64:65], v[60:63], off
	v_lshl_add_u64 v[64:65], v[80:81], 0, v[4:5]
	v_or_b32_e32 v4, v124, v55
	v_lshlrev_b32_e32 v4, 12, v4
	s_waitcnt lgkmcnt(6)
	v_cvt_pk_bf16_f32 v60, v66, v68
	s_waitcnt lgkmcnt(4)
	v_cvt_pk_bf16_f32 v61, v70, v72
	s_waitcnt lgkmcnt(2)
	v_cvt_pk_bf16_f32 v62, v74, v76
	s_waitcnt lgkmcnt(0)
	v_cvt_pk_bf16_f32 v63, v78, v82
	global_store_dwordx4 v[64:65], v[60:63], off
	v_lshl_add_u64 v[64:65], v[80:81], 0, v[4:5]
	s_nop 0
	v_cvt_pk_bf16_f32 v60, v67, v69
	v_cvt_pk_bf16_f32 v61, v71, v73
	v_cvt_pk_bf16_f32 v62, v75, v77
	v_cvt_pk_bf16_f32 v63, v79, v83
	global_store_dwordx4 v[64:65], v[60:63], off

; __device__ __forceinline__ void convT_tile(const float* __restrict__ W, int K, int N, bf16_t* __restrict__ WT, int tile, unsigned char* shm, int wave, int lane) {
;     const int ntn = N / 64, k0 = (tile / ntn) * 64, n0 = (tile % ntn) * 64;
;     float* T = (float*)shm + wave * (64 * 65);
;     { const int r4 = lane >> 4, c4 = (lane & 15) * 4;
; #pragma unroll
;       for (int i = 0; i < 16; ++i) { const int rr = 4 * i + r4; const float4 v = *(const float4*)(W + (size_t)(k0 + rr) * N + n0 + c4);
;           T[rr * 65 + c4] = v.x; T[rr * 65 + c4 + 1] = v.y; T[rr * 65 + c4 + 2] = v.z; T[rr * 65 + c4 + 3] = v.w; } }
; __device__ __forceinline__ void phase_lprep(PRef p, int layer, unsigned char* shm, const float* hL_, const float* hC_) {
;     ...
;         if (r < T_IN) { convT_tile(p.in[7] + (size_t)layer * 2048 * 5120, 2048, 5120, (bf16_t*)(p.ws + O_WT_IN), r, shm, wave, lane); continue; } r -= T_IN;
.LBB0_210:
	s_andn2_saveexec_b64 s[6:7], s[6:7]
	s_cbranch_execz .LBB0_195
	v_mul_hi_i32 v4, v58, s23
	v_lshrrev_b32_e32 v59, 31, v4
	v_ashrrev_i32_e32 v4, 5, v4
	v_add_u32_e32 v4, v4, v59
	v_mad_u64_u32 v[126:127], s[8:9], v4, s24, v[30:31]
	v_lshlrev_b32_e32 v124, 6, v4
	v_ashrrev_i32_e32 v127, 31, v126
	v_lshl_add_u64 v[120:121], v[126:127], 2, v[28:29]
	v_or_b32_e32 v4, v124, v1
	v_mad_i64_i32 v[68:69], s[8:9], v4, s25, v[120:121]
	v_or_b32_e32 v4, v124, v27
	v_mad_i64_i32 v[70:71], s[8:9], v4, s25, v[120:121]
	v_or_b32_e32 v4, v124, v31
	v_mad_i64_i32 v[76:77], s[8:9], v4, s25, v[120:121]
	v_or_b32_e32 v4, v124, v32
	v_mad_i64_i32 v[78:79], s[8:9], v4, s25, v[120:121]
	v_or_b32_e32 v4, v124, v33
	global_load_dwordx4 v[60:63], v[68:69], off nt
	global_load_dwordx4 v[64:67], v[70:71], off nt
	s_nop 0
	global_load_dwordx4 v[68:71], v[76:77], off nt
	global_load_dwordx4 v[72:75], v[78:79], off nt
	v_mad_i64_i32 v[76:77], s[8:9], v4, s25, v[120:121]
	v_or_b32_e32 v4, v124, v34
	global_load_dwordx4 v[76:79], v[76:77], off nt
	v_mad_i64_i32 v[80:81], s[8:9], v4, s25, v[120:121]
	global_load_dwordx4 v[80:83], v[80:81], off nt
	v_or_b32_e32 v4, v124, v36
	v_mad_i64_i32 v[84:85], s[8:9], v4, s25, v[120:121]
	global_load_dwordx4 v[84:87], v[84:85], off nt
	v_or_b32_e32 v4, v124, v37
	v_mad_i64_i32 v[88:89], s[8:9], v4, s25, v[120:121]
	global_load_dwordx4 v[88:91], v[88:89], off nt
	v_or_b32_e32 v4, v124, v38
	v_mad_i64_i32 v[92:93], s[8:9], v4, s25, v[120:121]
	global_load_dwordx4 v[92:95], v[92:93], off nt
	v_or_b32_e32 v4, v124, v39
	v_mad_i64_i32 v[96:97], s[8:9], v4, s25, v[120:121]
	v_or_b32_e32 v4, v124, v40
	global_load_dwordx4 v[96:99], v[96:97], off nt
	v_mad_i64_i32 v[100:101], s[8:9], v4, s25, v[120:121]
	global_load_dwordx4 v[100:103], v[100:101], off nt
	v_or_b32_e32 v4, v124, v42
	v_mad_i64_i32 v[104:105], s[8:9], v4, s25, v[120:121]
	global_load_dwordx4 v[104:107], v[104:105], off nt
	v_or_b32_e32 v4, v124, v43
	v_mad_i64_i32 v[108:109], s[8:9], v4, s25, v[120:121]
	global_load_dwordx4 v[108:111], v[108:109], off nt
	v_or_b32_e32 v4, v124, v44
	v_mad_i64_i32 v[112:113], s[8:9], v4, s25, v[120:121]
	global_load_dwordx4 v[112:115], v[112:113], off nt
	v_or_b32_e32 v4, v124, v45
	v_mad_i64_i32 v[116:117], s[8:9], v4, s25, v[120:121]
	global_load_dwordx4 v[116:119], v[116:117], off nt
	v_or_b32_e32 v4, v124, v46
	v_mad_i64_i32 v[120:121], s[8:9], v4, s25, v[120:121]
	global_load_dwordx4 v[120:123], v[120:121], off nt
	v_add_u32_e32 v4, v3, v25
	v_add_u32_e32 v59, 0x410, v4
	v_add_u32_e32 v125, 0x418, v4
	v_add_u32_e32 v127, 0x820, v4
	v_add_u32_e32 v128, 0x828, v4
	v_add_u32_e32 v129, 0xc30, v4
	v_add_u32_e32 v130, 0xc38, v4
	s_waitcnt vmcnt(15)
	ds_write2_b32 v4, v60, v61 offset1:1
	ds_write2_b32 v4, v62, v63 offset0:2 offset1:3
	s_waitcnt vmcnt(14)
	ds_write2_b32 v59, v64, v65 offset1:1
	ds_write2_b32 v125, v66, v67 offset1:1
	s_waitcnt vmcnt(13)
	ds_write2_b32 v127, v68, v69 offset1:1
	ds_write2_b32 v128, v70, v71 offset1:1
	s_waitcnt vmcnt(12)
	ds_write2_b32 v129, v72, v73 offset1:1
	ds_write2_b32 v130, v74, v75 offset1:1
	v_add_u32_e32 v59, 0x1040, v4
	v_ashrrev_i32_e32 v125, 31, v124
	s_waitcnt vmcnt(11)
	ds_write2_b32 v59, v76, v77 offset1:1
	v_add_u32_e32 v59, 0x1048, v4
	v_add_u32_e32 v4, 0x1450, v4
	s_waitcnt vmcnt(10)
	ds_write2_b32 v4, v80, v81 offset1:1
	v_add_u32_e32 v4, v3, v35
	ds_write2_b32 v59, v78, v79 offset1:1
	v_add_u32_e32 v59, 0x410, v4
	s_waitcnt vmcnt(9)
	ds_write2_b32 v59, v84, v85 offset1:1
	v_add_u32_e32 v59, 0x418, v4
	ds_write2_b32 v59, v86, v87 offset1:1
	v_add_u32_e32 v59, 0x820, v4
	s_waitcnt vmcnt(8)
	ds_write2_b32 v59, v88, v89 offset1:1
	v_add_u32_e32 v59, 0x828, v4
	ds_write2_b32 v59, v90, v91 offset1:1
	v_add_u32_e32 v59, 0xc30, v4
	s_waitcnt vmcnt(7)
	ds_write2_b32 v59, v92, v93 offset1:1
	v_add_u32_e32 v59, 0xc38, v4
	ds_write2_b32 v59, v94, v95 offset1:1
	v_add_u32_e32 v59, 0x1040, v4
	ds_write2_b32 v4, v82, v83 offset0:2 offset1:3
	s_waitcnt vmcnt(6)
	ds_write2_b32 v59, v96, v97 offset1:1
	v_add_u32_e32 v59, 0x1048, v4
	v_add_u32_e32 v4, 0x1450, v4
	s_waitcnt vmcnt(5)
	ds_write2_b32 v4, v100, v101 offset1:1
	v_add_u32_e32 v4, v3, v41
	ds_write2_b32 v59, v98, v99 offset1:1
	v_add_u32_e32 v59, 0x410, v4
	s_waitcnt vmcnt(4)
	ds_write2_b32 v59, v104, v105 offset1:1
	v_add_u32_e32 v59, 0x418, v4
	ds_write2_b32 v59, v106, v107 offset1:1
	v_add_u32_e32 v59, 0x820, v4
	s_waitcnt vmcnt(3)
	ds_write2_b32 v59, v108, v109 offset1:1
	v_add_u32_e32 v59, 0x828, v4
	ds_write2_b32 v59, v110, v111 offset1:1
	v_add_u32_e32 v59, 0xc30, v4
	s_waitcnt vmcnt(2)
	ds_write2_b32 v59, v112, v113 offset1:1
	v_add_u32_e32 v59, 0xc38, v4
	ds_write2_b32 v59, v114, v115 offset1:1
	v_add_u32_e32 v59, 0x1040, v4
	s_waitcnt vmcnt(1)
	ds_write2_b32 v59, v116, v117 offset1:1
	v_add_u32_e32 v59, 0x1048, v4
	ds_write2_b32 v4, v102, v103 offset0:2 offset1:3
	ds_write2_b32 v59, v118, v119 offset1:1
	v_add_u32_e32 v59, 0x1450, v4
	v_add_u32_e32 v4, 0x1458, v4
	s_waitcnt vmcnt(0)
; __device__ __forceinline__ unsigned cvt_pk_bf16(float lo, float hi) { unsigned r; asm("v_cvt_pk_bf16_f32 %0, %1, %2" : "=v"(r) : "v"(lo), "v"(hi)); return r; }
; __device__ __forceinline__ void convT_tile(const float* __restrict__ W, int K, int N, bf16_t* __restrict__ WT, int tile, unsigned char* shm, int wave, int lane) {
;     ...
;     __builtin_amdgcn_fence(__ATOMIC_RELEASE, "wavefront"); __builtin_amdgcn_wave_barrier(); __builtin_amdgcn_fence(__ATOMIC_ACQUIRE, "wavefront");
;     { const int n8 = lane >> 3, k8 = (lane & 7) * 8;
; #pragma unroll
;       for (int i = 0; i < 8; ++i) { const int n = 8 * i + n8; const float* sp = T + k8 * 65 + n;
;           u32x4 o; o.x = cvt_pk_bf16(sp[0], sp[65]); o.y = cvt_pk_bf16(sp[2 * 65], sp[3 * 65]); o.z = cvt_pk_bf16(sp[4 * 65], sp[5 * 65]); o.w = cvt_pk_bf16(sp[6 * 65], sp[7 * 65]);
;           *(u32x4*)(WT + (size_t)(n0 + n) * K + k0 + k8) = o; } }
;     __builtin_amdgcn_fence(__ATOMIC_RELEASE, "wavefront"); __builtin_amdgcn_wave_barrier(); __builtin_amdgcn_fence(__ATOMIC_ACQUIRE, "wavefront");
	ds_write2_b32 v4, v122, v123 offset1:1
	v_add_u32_e32 v4, 0x400, v48
	ds_write2_b32 v59, v120, v121 offset1:1
	ds_read2_b32 v[64:65], v48 offset0:65 offset1:73
	ds_read2_b32 v[66:67], v48 offset1:8
	ds_read2_b32 v[68:69], v48 offset0:130 offset1:138
	ds_read2_b32 v[70:71], v48 offset0:195 offset1:203
	ds_read2_b32 v[72:73], v4 offset0:4 offset1:12
	ds_read2_b32 v[74:75], v4 offset0:69 offset1:77
	ds_read2_b32 v[76:77], v4 offset0:134 offset1:142
	ds_read2_b32 v[78:79], v4 offset0:199 offset1:207
	v_add_u32_e32 v82, v126, v47
	v_ashrrev_i32_e32 v83, 31, v82
	v_lshl_add_u64 v[80:81], v[124:125], 1, v[8:9]
	v_lshlrev_b64 v[84:85], 12, v[82:83]
	s_waitcnt lgkmcnt(6)
	v_cvt_pk_bf16_f32 v60, v66, v64
	v_lshl_add_u64 v[84:85], v[80:81], 0, v[84:85]
	v_add_u32_e32 v64, 8, v82
	s_waitcnt lgkmcnt(4)
	v_cvt_pk_bf16_f32 v61, v68, v70
	s_waitcnt lgkmcnt(2)
	v_cvt_pk_bf16_f32 v62, v72, v74
	s_waitcnt lgkmcnt(0)
	v_cvt_pk_bf16_f32 v63, v76, v78
	global_store_dwordx4 v[84:85], v[60:63], off
	s_nop 1
	v_cvt_pk_bf16_f32 v60, v67, v65
	v_ashrrev_i32_e32 v65, 31, v64
	v_lshlrev_b64 v[64:65], 12, v[64:65]
	v_cvt_pk_bf16_f32 v61, v69, v71
	v_cvt_pk_bf16_f32 v62, v73, v75
	v_cvt_pk_bf16_f32 v63, v77, v79
	v_lshl_add_u64 v[64:65], v[80:81], 0, v[64:65]
	ds_read2_b32 v[66:67], v48 offset0:16 offset1:24
	ds_read2_b32 v[68:69], v48 offset0:81 offset1:89
	ds_read2_b32 v[70:71], v48 offset0:146 offset1:154
	ds_read2_b32 v[72:73], v48 offset0:211 offset1:219
	ds_read2_b32 v[74:75], v4 offset0:20 offset1:28
	ds_read2_b32 v[76:77], v4 offset0:85 offset1:93
	ds_read2_b32 v[78:79], v4 offset0:150 offset1:158
	ds_read2_b32 v[84:85], v4 offset0:215 offset1:223
	global_store_dwordx4 v[64:65], v[60:63], off
	v_add_u32_e32 v64, 16, v82
	v_ashrrev_i32_e32 v65, 31, v64
	v_lshlrev_b64 v[64:65], 12, v[64:65]
	v_lshl_add_u64 v[64:65], v[80:81], 0, v[64:65]
	s_waitcnt lgkmcnt(6)
	v_cvt_pk_bf16_f32 v60, v66, v68
	s_waitcnt lgkmcnt(4)
	v_cvt_pk_bf16_f32 v61, v70, v72
	s_waitcnt lgkmcnt(2)
	v_cvt_pk_bf16_f32 v62, v74, v76
	s_waitcnt lgkmcnt(0)
	v_cvt_pk_bf16_f32 v63, v78, v84
	global_store_dwordx4 v[64:65], v[60:63], off
	v_add_u32_e32 v64, 24, v82
	v_ashrrev_i32_e32 v65, 31, v64
	v_lshlrev_b64 v[64:65], 12, v[64:65]
	v_cvt_pk_bf16_f32 v60, v67, v69
	v_cvt_pk_bf16_f32 v61, v71, v73
	v_cvt_pk_bf16_f32 v62, v75, v77
	v_cvt_pk_bf16_f32 v63, v79, v85
	v_lshl_add_u64 v[64:65], v[80:81], 0, v[64:65]
	ds_read2_b32 v[66:67], v48 offset0:32 offset1:40
	ds_read2_b32 v[68:69], v48 offset0:97 offset1:105
	ds_read2_b32 v[70:71], v48 offset0:162 offset1:170
	ds_read2_b32 v[72:73], v48 offset0:227 offset1:235
	ds_read2_b32 v[74:75], v4 offset0:36 offset1:44
	ds_read2_b32 v[76:77], v4 offset0:101 offset1:109
	ds_read2_b32 v[78:79], v4 offset0:166 offset1:174
	ds_read2_b32 v[84:85], v4 offset0:231 offset1:239
	global_store_dwordx4 v[64:65], v[60:63], off
	v_add_u32_e32 v64, 32, v82
	v_ashrrev_i32_e32 v65, 31, v64
	v_lshlrev_b64 v[64:65], 12, v[64:65]
	v_lshl_add_u64 v[64:65], v[80:81], 0, v[64:65]
	s_waitcnt lgkmcnt(6)
	v_cvt_pk_bf16_f32 v60, v66, v68
	s_waitcnt lgkmcnt(4)
	v_cvt_pk_bf16_f32 v61, v70, v72
	s_waitcnt lgkmcnt(2)
	v_cvt_pk_bf16_f32 v62, v74, v76
	s_waitcnt lgkmcnt(0)
	v_cvt_pk_bf16_f32 v63, v78, v84
	global_store_dwordx4 v[64:65], v[60:63], off
	v_add_u32_e32 v64, 40, v82
	v_ashrrev_i32_e32 v65, 31, v64
	v_lshlrev_b64 v[64:65], 12, v[64:65]
	v_cvt_pk_bf16_f32 v60, v67, v69
	v_cvt_pk_bf16_f32 v61, v71, v73
	v_cvt_pk_bf16_f32 v62, v75, v77
	v_cvt_pk_bf16_f32 v63, v79, v85
	v_lshl_add_u64 v[64:65], v[80:81], 0, v[64:65]
	ds_read2_b32 v[66:67], v48 offset0:48 offset1:56
	ds_read2_b32 v[68:69], v48 offset0:113 offset1:121
	ds_read2_b32 v[70:71], v48 offset0:178 offset1:186
	ds_read2_b32 v[72:73], v48 offset0:243 offset1:251
	ds_read2_b32 v[74:75], v4 offset0:52 offset1:60
	ds_read2_b32 v[76:77], v4 offset0:117 offset1:125
	ds_read2_b32 v[78:79], v4 offset0:182 offset1:190
	ds_read2_b32 v[84:85], v4 offset0:247 offset1:255
	global_store_dwordx4 v[64:65], v[60:63], off
	v_add_u32_e32 v64, 48, v82
	v_ashrrev_i32_e32 v65, 31, v64
	v_lshlrev_b64 v[64:65], 12, v[64:65]
	v_lshl_add_u64 v[64:65], v[80:81], 0, v[64:65]
	s_waitcnt lgkmcnt(6)
	v_cvt_pk_bf16_f32 v60, v66, v68
	s_waitcnt lgkmcnt(4)
	v_cvt_pk_bf16_f32 v61, v70, v72
	s_waitcnt lgkmcnt(2)
	v_cvt_pk_bf16_f32 v62, v74, v76
	s_waitcnt lgkmcnt(0)
	v_cvt_pk_bf16_f32 v63, v78, v84
	global_store_dwordx4 v[64:65], v[60:63], off
	v_add_u32_e32 v64, 56, v82
	v_ashrrev_i32_e32 v65, 31, v64
	v_lshlrev_b64 v[64:65], 12, v[64:65]
	v_lshl_add_u64 v[64:65], v[80:81], 0, v[64:65]
	v_cvt_pk_bf16_f32 v60, v67, v69
	v_cvt_pk_bf16_f32 v61, v71, v73
	v_cvt_pk_bf16_f32 v62, v75, v77
	v_cvt_pk_bf16_f32 v63, v79, v85
	global_store_dwordx4 v[64:65], v[60:63], off
	s_branch .LBB0_195

; __device__ __forceinline__ void convT_tile(const float* __restrict__ W, int K, int N, bf16_t* __restrict__ WT, int tile, unsigned char* shm, int wave, int lane) {
;     const int ntn = N / 64, k0 = (tile / ntn) * 64, n0 = (tile % ntn) * 64;
;     float* T = (float*)shm + wave * (64 * 65);
;     { const int r4 = lane >> 4, c4 = (lane & 15) * 4;
; #pragma unroll
;       for (int i = 0; i < 16; ++i) { const int rr = 4 * i + r4; const float4 v = *(const float4*)(W + (size_t)(k0 + rr) * N + n0 + c4);
;           T[rr * 65 + c4] = v.x; T[rr * 65 + c4 + 1] = v.y; T[rr * 65 + c4 + 2] = v.z; T[rr * 65 + c4 + 3] = v.w; } }
; __device__ __forceinline__ void phase_lprep(PRef p, int layer, unsigned char* shm, const float* hL_, const float* hC_) {
;     constexpr int N_S5 = 128, T_IN = 32 * 80, T_OUT = 32 * 32, T_UP = 32 * 176, T_DOWN = 88 * 32, T_GLU = 64;
;     const int tid = otid(), wave = tid >> 6, lane = tid & 63, gw = blockIdx.x * 8 + wave, ngw = gridDim.x * 8;
;     for (int rep = 0; rep < NREP(11); ++rep)
;     for (int it = blockIdx.x; it < 384 + N_S5; it += gridDim.x) {
;         int r = it;
;         if (r >= 256 && r < 384) continue;
;         if (r < 256) {
;     ...
;             const bool isctx = r >= 128; const int q = r & 127; if (!isctx || layer == 0) hyfilter_item(p, layer, isctx, q, shm);
;     ...
;             continue; }
;         r -= 384;
;     ...
;         s5prep_item(p, layer, r >> 2, r & 3, shm);
;     ...
;     }
;     __syncthreads();
;     constexpr int NT = T_IN + T_OUT + T_UP + T_DOWN + T_GLU;
;     for (int rep = 0; rep < NREP(12); ++rep)
;     for (int it = gw; it < NT; it += ngw) {
;         int r = it;
;         if (r < T_IN) { convT_tile(p.in[7] + (size_t)layer * 2048 * 5120, 2048, 5120, (bf16_t*)(p.ws + O_WT_IN), r, shm, wave, lane); continue; } r -= T_IN;
;         if (r < T_OUT) { convT_tile(p.in[28] + (size_t)layer * 2048 * 2048, 2048, 2048, (bf16_t*)(p.ws + O_WT_OUT), r, shm, wave, lane); continue; } r -= T_OUT;
;         if (r < T_UP) { convT_tile(p.in[30] + (size_t)layer * 2048 * 11264, 2048, 11264, (bf16_t*)(p.ws + O_WT_UP), r, shm, wave, lane); continue; } r -= T_UP;
;         if (r < T_DOWN) { convT_tile(p.in[33] + (size_t)layer * 5632 * 2048, 5632, 2048, (bf16_t*)(p.ws + O_WT_DOWN), r, shm, wave, lane); continue; } r -= T_DOWN;
;         convT_tile(p.in[26] + (size_t)layer * 512 * 512, 512, 512, (bf16_t*)(p.ws + O_WT_GLU), r, shm, wave, lane);
.LBB0_749:
	v_cmp_lt_i32_e32 vcc, s14, v58
	s_and_saveexec_b64 s[10:11], vcc
	s_xor_b64 s[10:11], exec, s[10:11]
	s_cbranch_execz .LBB0_763
	v_cmp_lt_u32_e32 vcc, s22, v58
	s_and_saveexec_b64 s[16:17], vcc
	s_xor_b64 s[16:17], exec, s[16:17]
	s_cbranch_execz .LBB0_760
	v_cmp_lt_u32_e32 vcc, s23, v58
	s_and_saveexec_b64 s[18:19], vcc
	s_xor_b64 s[18:19], exec, s[18:19]
	s_cbranch_execz .LBB0_757
	v_cmp_lt_u32_e32 vcc, s24, v58
	s_and_saveexec_b64 s[20:21], vcc
	s_xor_b64 s[20:21], exec, s[20:21]
	s_cbranch_execz .LBB0_754
	v_and_b32_e32 v124, 0x1c0, v26
	v_and_b32_e32 v59, 0x7c0, v57
	v_lshlrev_b32_e32 v4, 2, v124
	v_lshl_add_u64 v[120:121], v[6:7], 0, v[4:5]
	v_or_b32_e32 v4, v59, v1
	v_lshlrev_b32_e32 v4, 11, v4
	v_lshl_add_u64 v[60:61], v[120:121], 0, v[4:5]
	v_or_b32_e32 v4, v59, v29
	v_lshlrev_b32_e32 v4, 11, v4
	v_lshl_add_u64 v[64:65], v[120:121], 0, v[4:5]
	v_or_b32_e32 v4, v59, v31
	v_lshlrev_b32_e32 v4, 11, v4
	v_lshl_add_u64 v[68:69], v[120:121], 0, v[4:5]
	v_or_b32_e32 v4, v59, v32
	v_lshlrev_b32_e32 v4, 11, v4
	v_lshl_add_u64 v[72:73], v[120:121], 0, v[4:5]
	v_or_b32_e32 v4, v59, v33
	v_lshlrev_b32_e32 v4, 11, v4
	v_lshl_add_u64 v[76:77], v[120:121], 0, v[4:5]
	v_or_b32_e32 v4, v59, v34
	v_lshlrev_b32_e32 v4, 11, v4
	v_lshl_add_u64 v[80:81], v[120:121], 0, v[4:5]
	v_or_b32_e32 v4, v59, v36
	v_lshlrev_b32_e32 v4, 11, v4
	global_load_dwordx4 v[60:63], v[60:61], off nt
	s_nop 0
	global_load_dwordx4 v[64:67], v[64:65], off nt
	s_nop 0
	global_load_dwordx4 v[68:71], v[68:69], off nt
	s_nop 0
	global_load_dwordx4 v[72:75], v[72:73], off nt
	s_nop 0
	global_load_dwordx4 v[76:79], v[76:77], off nt
	s_nop 0
	global_load_dwordx4 v[80:83], v[80:81], off nt
	v_lshl_add_u64 v[84:85], v[120:121], 0, v[4:5]
	v_or_b32_e32 v4, v59, v37
	global_load_dwordx4 v[84:87], v[84:85], off nt
	v_lshlrev_b32_e32 v4, 11, v4
	v_lshl_add_u64 v[88:89], v[120:121], 0, v[4:5]
	v_or_b32_e32 v4, v59, v38
	global_load_dwordx4 v[88:91], v[88:89], off nt
	v_lshlrev_b32_e32 v4, 11, v4
	v_lshl_add_u64 v[92:93], v[120:121], 0, v[4:5]
	v_or_b32_e32 v4, v59, v39
	global_load_dwordx4 v[92:95], v[92:93], off nt
	v_lshlrev_b32_e32 v4, 11, v4
	v_lshl_add_u64 v[96:97], v[120:121], 0, v[4:5]
	v_or_b32_e32 v4, v59, v40
	global_load_dwordx4 v[96:99], v[96:97], off nt
	v_lshlrev_b32_e32 v4, 11, v4
	v_lshl_add_u64 v[100:101], v[120:121], 0, v[4:5]
	v_or_b32_e32 v4, v59, v42
	global_load_dwordx4 v[100:103], v[100:101], off nt
	v_lshlrev_b32_e32 v4, 11, v4
	v_lshl_add_u64 v[104:105], v[120:121], 0, v[4:5]
	v_or_b32_e32 v4, v59, v43
	global_load_dwordx4 v[104:107], v[104:105], off nt
	v_lshlrev_b32_e32 v4, 11, v4
	v_lshl_add_u64 v[108:109], v[120:121], 0, v[4:5]
	v_or_b32_e32 v4, v59, v44
	global_load_dwordx4 v[108:111], v[108:109], off nt
	v_lshlrev_b32_e32 v4, 11, v4
	v_lshl_add_u64 v[112:113], v[120:121], 0, v[4:5]
	v_or_b32_e32 v4, v59, v45
	global_load_dwordx4 v[112:115], v[112:113], off nt
	v_lshlrev_b32_e32 v4, 11, v4
	v_lshl_add_u64 v[116:117], v[120:121], 0, v[4:5]
	v_or_b32_e32 v4, v59, v46
	global_load_dwordx4 v[116:119], v[116:117], off nt
	v_lshlrev_b32_e32 v4, 11, v4
	v_lshl_add_u64 v[120:121], v[120:121], 0, v[4:5]
	global_load_dwordx4 v[120:123], v[120:121], off nt
	v_add_u32_e32 v4, v3, v27
	v_add_u32_e32 v125, v3, v35
	v_add_u32_e32 v126, 0x410, v4
	v_add_u32_e32 v127, 0x418, v4
	v_add_u32_e32 v128, 0x820, v4
	v_add_u32_e32 v129, 0x828, v4
	v_add_u32_e32 v130, 0xc30, v4
	v_add_u32_e32 v131, 0xc38, v4
	v_add_u32_e32 v132, 0x1040, v4
	v_add_u32_e32 v133, 0x1048, v4
	v_add_u32_e32 v134, 0x1450, v4
	s_waitcnt vmcnt(15)
	ds_write2_b32 v4, v60, v61 offset1:1
	ds_write2_b32 v4, v62, v63 offset0:2 offset1:3
	s_waitcnt vmcnt(14)
	ds_write2_b32 v126, v64, v65 offset1:1
	ds_write2_b32 v127, v66, v67 offset1:1
	s_waitcnt vmcnt(13)
	ds_write2_b32 v128, v68, v69 offset1:1
	ds_write2_b32 v129, v70, v71 offset1:1
	s_waitcnt vmcnt(12)
	ds_write2_b32 v130, v72, v73 offset1:1
	ds_write2_b32 v131, v74, v75 offset1:1
	s_waitcnt vmcnt(11)
	ds_write2_b32 v132, v76, v77 offset1:1
	ds_write2_b32 v133, v78, v79 offset1:1
	s_waitcnt vmcnt(10)
	ds_write2_b32 v134, v80, v81 offset1:1
	ds_write2_b32 v125, v82, v83 offset0:2 offset1:3
	v_add_u32_e32 v4, 0x410, v125
	s_waitcnt vmcnt(9)
	ds_write2_b32 v4, v84, v85 offset1:1
	v_add_u32_e32 v4, 0x418, v125
	ds_write2_b32 v4, v86, v87 offset1:1
	v_add_u32_e32 v4, 0x820, v125
	s_waitcnt vmcnt(8)
	ds_write2_b32 v4, v88, v89 offset1:1
	v_add_u32_e32 v4, 0x828, v125
	ds_write2_b32 v4, v90, v91 offset1:1
	v_add_u32_e32 v4, 0xc30, v125
	s_waitcnt vmcnt(7)
	ds_write2_b32 v4, v92, v93 offset1:1
	v_add_u32_e32 v4, 0xc38, v125
	ds_write2_b32 v4, v94, v95 offset1:1
	v_add_u32_e32 v4, 0x1040, v125
	s_waitcnt vmcnt(6)
	ds_write2_b32 v4, v96, v97 offset1:1
	v_add_u32_e32 v4, 0x1048, v125
	ds_write2_b32 v4, v98, v99 offset1:1
	v_add_u32_e32 v4, 0x1450, v125
	s_waitcnt vmcnt(5)
	ds_write2_b32 v4, v100, v101 offset1:1
	v_add_u32_e32 v4, v3, v41
	v_add_u32_e32 v60, 0x410, v4
	ds_write2_b32 v4, v102, v103 offset0:2 offset1:3
	s_waitcnt vmcnt(4)
	ds_write2_b32 v60, v104, v105 offset1:1
	v_add_u32_e32 v60, 0x418, v4
	ds_write2_b32 v60, v106, v107 offset1:1
	v_add_u32_e32 v60, 0x820, v4
	s_waitcnt vmcnt(3)
	ds_write2_b32 v60, v108, v109 offset1:1
	v_add_u32_e32 v60, 0x828, v4
	ds_write2_b32 v60, v110, v111 offset1:1
	v_add_u32_e32 v60, 0xc30, v4
	s_waitcnt vmcnt(2)
	ds_write2_b32 v60, v112, v113 offset1:1
	v_add_u32_e32 v60, 0xc38, v4
	ds_write2_b32 v60, v114, v115 offset1:1
	v_add_u32_e32 v60, 0x1040, v4
	s_waitcnt vmcnt(1)
	ds_write2_b32 v60, v116, v117 offset1:1
	v_add_u32_e32 v60, 0x1048, v4
	ds_write2_b32 v60, v118, v119 offset1:1
	v_add_u32_e32 v60, 0x1450, v4
	v_add_u32_e32 v4, 0x1458, v4
	s_waitcnt vmcnt(0)
; __device__ __forceinline__ unsigned cvt_pk_bf16(float lo, float hi) { unsigned r; asm("v_cvt_pk_bf16_f32 %0, %1, %2" : "=v"(r) : "v"(lo), "v"(hi)); return r; }
; __device__ __forceinline__ void convT_tile(const float* __restrict__ W, int K, int N, bf16_t* __restrict__ WT, int tile, unsigned char* shm, int wave, int lane) {
;     ...
;     __builtin_amdgcn_fence(__ATOMIC_RELEASE, "wavefront"); __builtin_amdgcn_wave_barrier(); __builtin_amdgcn_fence(__ATOMIC_ACQUIRE, "wavefront");
;     { const int n8 = lane >> 3, k8 = (lane & 7) * 8;
; #pragma unroll
;       for (int i = 0; i < 8; ++i) { const int n = 8 * i + n8; const float* sp = T + k8 * 65 + n;
;           u32x4 o; o.x = cvt_pk_bf16(sp[0], sp[65]); o.y = cvt_pk_bf16(sp[2 * 65], sp[3 * 65]); o.z = cvt_pk_bf16(sp[4 * 65], sp[5 * 65]); o.w = cvt_pk_bf16(sp[6 * 65], sp[7 * 65]);
;           *(u32x4*)(WT + (size_t)(n0 + n) * K + k0 + k8) = o; } }
;     __builtin_amdgcn_fence(__ATOMIC_RELEASE, "wavefront"); __builtin_amdgcn_wave_barrier(); __builtin_amdgcn_fence(__ATOMIC_ACQUIRE, "wavefront");
	ds_write2_b32 v4, v122, v123 offset1:1
	v_lshlrev_b32_e32 v4, 1, v59
	v_add_u32_e32 v59, 0x400, v48
	ds_write2_b32 v60, v120, v121 offset1:1
	ds_read2_b32 v[64:65], v48 offset0:65 offset1:73
	ds_read2_b32 v[66:67], v48 offset1:8
	ds_read2_b32 v[68:69], v48 offset0:130 offset1:138
	ds_read2_b32 v[70:71], v48 offset0:195 offset1:203
	ds_read2_b32 v[72:73], v59 offset0:4 offset1:12
	ds_read2_b32 v[74:75], v59 offset0:69 offset1:77
	ds_read2_b32 v[76:77], v59 offset0:134 offset1:142
	ds_read2_b32 v[78:79], v59 offset0:199 offset1:207
	v_lshl_add_u64 v[80:81], v[10:11], 0, v[4:5]
	v_or_b32_e32 v4, v124, v47
	v_lshlrev_b32_e32 v4, 10, v4
	v_lshl_add_u64 v[82:83], v[80:81], 0, v[4:5]
	s_waitcnt lgkmcnt(6)
	v_cvt_pk_bf16_f32 v60, v66, v64
	s_waitcnt lgkmcnt(4)
	v_cvt_pk_bf16_f32 v61, v68, v70
	s_waitcnt lgkmcnt(2)
	v_cvt_pk_bf16_f32 v62, v72, v74
	s_waitcnt lgkmcnt(0)
	v_cvt_pk_bf16_f32 v63, v76, v78
	global_store_dwordx4 v[82:83], v[60:63], off
	v_or_b32_e32 v4, v124, v49
	v_lshlrev_b32_e32 v4, 10, v4
	v_cvt_pk_bf16_f32 v60, v67, v65
	v_cvt_pk_bf16_f32 v61, v69, v71
	v_cvt_pk_bf16_f32 v62, v73, v75
	v_cvt_pk_bf16_f32 v63, v77, v79
	ds_read2_b32 v[66:67], v48 offset0:16 offset1:24
	ds_read2_b32 v[68:69], v48 offset0:81 offset1:89
	ds_read2_b32 v[70:71], v48 offset0:146 offset1:154
	ds_read2_b32 v[72:73], v48 offset0:211 offset1:219
	ds_read2_b32 v[74:75], v59 offset0:20 offset1:28
	ds_read2_b32 v[76:77], v59 offset0:85 offset1:93
	ds_read2_b32 v[78:79], v59 offset0:150 offset1:158
	ds_read2_b32 v[82:83], v59 offset0:215 offset1:223
	v_lshl_add_u64 v[64:65], v[80:81], 0, v[4:5]
	v_or_b32_e32 v4, v124, v50
	v_lshlrev_b32_e32 v4, 10, v4
	global_store_dwordx4 v[64:65], v[60:63], off
	v_lshl_add_u64 v[64:65], v[80:81], 0, v[4:5]
	v_or_b32_e32 v4, v124, v51
	s_waitcnt lgkmcnt(6)
	v_cvt_pk_bf16_f32 v60, v66, v68
	s_waitcnt lgkmcnt(4)
	v_cvt_pk_bf16_f32 v61, v70, v72
	s_waitcnt lgkmcnt(2)
	v_cvt_pk_bf16_f32 v62, v74, v76
	s_waitcnt lgkmcnt(0)
	v_cvt_pk_bf16_f32 v63, v78, v82
	global_store_dwordx4 v[64:65], v[60:63], off
	v_lshlrev_b32_e32 v4, 10, v4
	v_lshl_add_u64 v[64:65], v[80:81], 0, v[4:5]
	v_cvt_pk_bf16_f32 v60, v67, v69
	v_cvt_pk_bf16_f32 v61, v71, v73
	v_cvt_pk_bf16_f32 v62, v75, v77
	v_cvt_pk_bf16_f32 v63, v79, v83
	ds_read2_b32 v[66:67], v48 offset0:32 offset1:40
	ds_read2_b32 v[68:69], v48 offset0:97 offset1:105
	ds_read2_b32 v[70:71], v48 offset0:162 offset1:170
	ds_read2_b32 v[72:73], v48 offset0:227 offset1:235
	ds_read2_b32 v[74:75], v59 offset0:36 offset1:44
	ds_read2_b32 v[76:77], v59 offset0:101 offset1:109
	ds_read2_b32 v[78:79], v59 offset0:166 offset1:174
	ds_read2_b32 v[82:83], v59 offset0:231 offset1:239
	v_or_b32_e32 v4, v124, v52
	v_lshlrev_b32_e32 v4, 10, v4
	global_store_dwordx4 v[64:65], v[60:63], off
	v_lshl_add_u64 v[64:65], v[80:81], 0, v[4:5]
	v_or_b32_e32 v4, v124, v53
	s_waitcnt lgkmcnt(6)
	v_cvt_pk_bf16_f32 v60, v66, v68
	s_waitcnt lgkmcnt(4)
	v_cvt_pk_bf16_f32 v61, v70, v72
	s_waitcnt lgkmcnt(2)
	v_cvt_pk_bf16_f32 v62, v74, v76
	s_waitcnt lgkmcnt(0)
	v_cvt_pk_bf16_f32 v63, v78, v82
	global_store_dwordx4 v[64:65], v[60:63], off
	v_lshlrev_b32_e32 v4, 10, v4
	v_lshl_add_u64 v[64:65], v[80:81], 0, v[4:5]
	v_cvt_pk_bf16_f32 v60, v67, v69
	v_cvt_pk_bf16_f32 v61, v71, v73
	v_cvt_pk_bf16_f32 v62, v75, v77
	v_cvt_pk_bf16_f32 v63, v79, v83
	ds_read2_b32 v[66:67], v48 offset0:48 offset1:56
	ds_read2_b32 v[68:69], v48 offset0:113 offset1:121
	ds_read2_b32 v[70:71], v48 offset0:178 offset1:186
	ds_read2_b32 v[72:73], v48 offset0:243 offset1:251
	ds_read2_b32 v[74:75], v59 offset0:52 offset1:60
	ds_read2_b32 v[76:77], v59 offset0:117 offset1:125
	ds_read2_b32 v[78:79], v59 offset0:182 offset1:190
	ds_read2_b32 v[82:83], v59 offset0:247 offset1:255
	v_or_b32_e32 v4, v124, v54
	v_lshlrev_b32_e32 v4, 10, v4
	global_store_dwordx4 v[64:65], v[60:63], off
	v_lshl_add_u64 v[64:65], v[80:81], 0, v[4:5]
	v_or_b32_e32 v4, v124, v55
	v_lshlrev_b32_e32 v4, 10, v4
	s_waitcnt lgkmcnt(6)
	v_cvt_pk_bf16_f32 v60, v66, v68
	s_waitcnt lgkmcnt(4)
	v_cvt_pk_bf16_f32 v61, v70, v72
	s_waitcnt lgkmcnt(2)
	v_cvt_pk_bf16_f32 v62, v74, v76
	s_waitcnt lgkmcnt(0)
	v_cvt_pk_bf16_f32 v63, v78, v82
	global_store_dwordx4 v[64:65], v[60:63], off
	v_lshl_add_u64 v[64:65], v[80:81], 0, v[4:5]
	s_nop 0
	v_cvt_pk_bf16_f32 v60, v67, v69
	v_cvt_pk_bf16_f32 v61, v71, v73
	v_cvt_pk_bf16_f32 v62, v75, v77
	v_cvt_pk_bf16_f32 v63, v79, v83
	global_store_dwordx4 v[64:65], v[60:63], off
; __device__ __forceinline__ void convT_tile(const float* __restrict__ W, int K, int N, bf16_t* __restrict__ WT, int tile, unsigned char* shm, int wave, int lane) {
;     const int ntn = N / 64, k0 = (tile / ntn) * 64, n0 = (tile % ntn) * 64;
;     float* T = (float*)shm + wave * (64 * 65);
;     { const int r4 = lane >> 4, c4 = (lane & 15) * 4;
; #pragma unroll
;       for (int i = 0; i < 16; ++i) { const int rr = 4 * i + r4; const float4 v = *(const float4*)(W + (size_t)(k0 + rr) * N + n0 + c4);
;           T[rr * 65 + c4] = v.x; T[rr * 65 + c4 + 1] = v.y; T[rr * 65 + c4 + 2] = v.z; T[rr * 65 + c4 + 3] = v.w; } }
; __device__ __forceinline__ void phase_lprep(PRef p, int layer, unsigned char* shm, const float* hL_, const float* hC_) {
;     ...
;         if (r < T_DOWN) { convT_tile(p.in[33] + (size_t)layer * 5632 * 2048, 5632, 2048, (bf16_t*)(p.ws + O_WT_DOWN), r, shm, wave, lane); continue; } r -= T_DOWN;
.LBB0_754:
	s_andn2_saveexec_b64 s[20:21], s[20:21]
	s_cbranch_execz .LBB0_756
	v_and_b32_e32 v124, 0x7c0, v26
	v_and_b32_e32 v59, 0x1ffc0, v56
	v_lshlrev_b32_e32 v4, 2, v124
	v_lshl_add_u64 v[120:121], v[12:13], 0, v[4:5]
	v_or_b32_e32 v4, v59, v1
	v_lshlrev_b32_e32 v4, 13, v4
	v_lshl_add_u64 v[60:61], v[120:121], 0, v[4:5]
	v_or_b32_e32 v4, v59, v29
	v_lshlrev_b32_e32 v4, 13, v4
	v_lshl_add_u64 v[64:65], v[120:121], 0, v[4:5]
	v_or_b32_e32 v4, v59, v31
	v_lshlrev_b32_e32 v4, 13, v4
	v_lshl_add_u64 v[68:69], v[120:121], 0, v[4:5]
	v_or_b32_e32 v4, v59, v32
	v_lshlrev_b32_e32 v4, 13, v4
	v_lshl_add_u64 v[72:73], v[120:121], 0, v[4:5]
	v_or_b32_e32 v4, v59, v33
	v_lshlrev_b32_e32 v4, 13, v4
	v_lshl_add_u64 v[76:77], v[120:121], 0, v[4:5]
	v_or_b32_e32 v4, v59, v34
	v_lshlrev_b32_e32 v4, 13, v4
	v_lshl_add_u64 v[80:81], v[120:121], 0, v[4:5]
	v_or_b32_e32 v4, v59, v36
	v_lshlrev_b32_e32 v4, 13, v4
	global_load_dwordx4 v[60:63], v[60:61], off nt
	s_nop 0
	global_load_dwordx4 v[64:67], v[64:65], off nt
	s_nop 0
	global_load_dwordx4 v[68:71], v[68:69], off nt
	s_nop 0
	global_load_dwordx4 v[72:75], v[72:73], off nt
	s_nop 0
	global_load_dwordx4 v[76:79], v[76:77], off nt
	s_nop 0
	global_load_dwordx4 v[80:83], v[80:81], off nt
	v_lshl_add_u64 v[84:85], v[120:121], 0, v[4:5]
	v_or_b32_e32 v4, v59, v37
	global_load_dwordx4 v[84:87], v[84:85], off nt
	v_lshlrev_b32_e32 v4, 13, v4
	v_lshl_add_u64 v[88:89], v[120:121], 0, v[4:5]
	v_or_b32_e32 v4, v59, v38
	global_load_dwordx4 v[88:91], v[88:89], off nt
	v_lshlrev_b32_e32 v4, 13, v4
	v_lshl_add_u64 v[92:93], v[120:121], 0, v[4:5]
	v_or_b32_e32 v4, v59, v39
	global_load_dwordx4 v[92:95], v[92:93], off nt
	v_lshlrev_b32_e32 v4, 13, v4
	v_lshl_add_u64 v[96:97], v[120:121], 0, v[4:5]
	v_or_b32_e32 v4, v59, v40
	global_load_dwordx4 v[96:99], v[96:97], off nt
	v_lshlrev_b32_e32 v4, 13, v4
	v_lshl_add_u64 v[100:101], v[120:121], 0, v[4:5]
	v_or_b32_e32 v4, v59, v42
	global_load_dwordx4 v[100:103], v[100:101], off nt
	v_lshlrev_b32_e32 v4, 13, v4
	v_lshl_add_u64 v[104:105], v[120:121], 0, v[4:5]
	v_or_b32_e32 v4, v59, v43
	global_load_dwordx4 v[104:107], v[104:105], off nt
	v_lshlrev_b32_e32 v4, 13, v4
	v_lshl_add_u64 v[108:109], v[120:121], 0, v[4:5]
	v_or_b32_e32 v4, v59, v44
	global_load_dwordx4 v[108:111], v[108:109], off nt
	v_lshlrev_b32_e32 v4, 13, v4
	v_lshl_add_u64 v[112:113], v[120:121], 0, v[4:5]
	v_or_b32_e32 v4, v59, v45
	global_load_dwordx4 v[112:115], v[112:113], off nt
	v_lshlrev_b32_e32 v4, 13, v4
	v_lshl_add_u64 v[116:117], v[120:121], 0, v[4:5]
	v_or_b32_e32 v4, v59, v46
	global_load_dwordx4 v[116:119], v[116:117], off nt
	v_lshlrev_b32_e32 v4, 13, v4
	v_lshl_add_u64 v[120:121], v[120:121], 0, v[4:5]
	global_load_dwordx4 v[120:123], v[120:121], off nt
	v_add_u32_e32 v4, v3, v27
	v_add_u32_e32 v125, v3, v35
	v_add_u32_e32 v126, 0x410, v4
	v_add_u32_e32 v127, 0x418, v4
	v_add_u32_e32 v128, 0x820, v4
	v_add_u32_e32 v129, 0x828, v4
	v_add_u32_e32 v130, 0xc30, v4
	v_add_u32_e32 v131, 0xc38, v4
	v_add_u32_e32 v132, 0x1040, v4
	v_add_u32_e32 v133, 0x1048, v4
	v_add_u32_e32 v134, 0x1450, v4
	s_waitcnt vmcnt(15)
	ds_write2_b32 v4, v60, v61 offset1:1
	ds_write2_b32 v4, v62, v63 offset0:2 offset1:3
	s_waitcnt vmcnt(14)
	ds_write2_b32 v126, v64, v65 offset1:1
	ds_write2_b32 v127, v66, v67 offset1:1
	s_waitcnt vmcnt(13)
	ds_write2_b32 v128, v68, v69 offset1:1
	ds_write2_b32 v129, v70, v71 offset1:1
	s_waitcnt vmcnt(12)
	ds_write2_b32 v130, v72, v73 offset1:1
	ds_write2_b32 v131, v74, v75 offset1:1
	s_waitcnt vmcnt(11)
	ds_write2_b32 v132, v76, v77 offset1:1
	ds_write2_b32 v133, v78, v79 offset1:1
	s_waitcnt vmcnt(10)
	ds_write2_b32 v134, v80, v81 offset1:1
	ds_write2_b32 v125, v82, v83 offset0:2 offset1:3
	v_add_u32_e32 v4, 0x410, v125
	s_waitcnt vmcnt(9)
	ds_write2_b32 v4, v84, v85 offset1:1
	v_add_u32_e32 v4, 0x418, v125
	ds_write2_b32 v4, v86, v87 offset1:1
	v_add_u32_e32 v4, 0x820, v125
	s_waitcnt vmcnt(8)
	ds_write2_b32 v4, v88, v89 offset1:1
	v_add_u32_e32 v4, 0x828, v125
	ds_write2_b32 v4, v90, v91 offset1:1
	v_add_u32_e32 v4, 0xc30, v125
	s_waitcnt vmcnt(7)
	ds_write2_b32 v4, v92, v93 offset1:1
	v_add_u32_e32 v4, 0xc38, v125
	ds_write2_b32 v4, v94, v95 offset1:1
	v_add_u32_e32 v4, 0x1040, v125
	s_waitcnt vmcnt(6)
	ds_write2_b32 v4, v96, v97 offset1:1
	v_add_u32_e32 v4, 0x1048, v125
	ds_write2_b32 v4, v98, v99 offset1:1
	v_add_u32_e32 v4, 0x1450, v125
	s_waitcnt vmcnt(5)
	ds_write2_b32 v4, v100, v101 offset1:1
	v_add_u32_e32 v4, v3, v41
	v_add_u32_e32 v60, 0x410, v4
	ds_write2_b32 v4, v102, v103 offset0:2 offset1:3
	s_waitcnt vmcnt(4)
	ds_write2_b32 v60, v104, v105 offset1:1
	v_add_u32_e32 v60, 0x418, v4
	ds_write2_b32 v60, v106, v107 offset1:1
	v_add_u32_e32 v60, 0x820, v4
	s_waitcnt vmcnt(3)
	ds_write2_b32 v60, v108, v109 offset1:1
	v_add_u32_e32 v60, 0x828, v4
	ds_write2_b32 v60, v110, v111 offset1:1
	v_add_u32_e32 v60, 0xc30, v4
	s_waitcnt vmcnt(2)
	ds_write2_b32 v60, v112, v113 offset1:1
	v_add_u32_e32 v60, 0xc38, v4
	ds_write2_b32 v60, v114, v115 offset1:1
	v_add_u32_e32 v60, 0x1040, v4
	s_waitcnt vmcnt(1)
; __device__ __forceinline__ unsigned cvt_pk_bf16(float lo, float hi) { unsigned r; asm("v_cvt_pk_bf16_f32 %0, %1, %2" : "=v"(r) : "v"(lo), "v"(hi)); return r; }
; __device__ __forceinline__ void convT_tile(const float* __restrict__ W, int K, int N, bf16_t* __restrict__ WT, int tile, unsigned char* shm, int wave, int lane) {
;     ...
;     __builtin_amdgcn_fence(__ATOMIC_RELEASE, "wavefront"); __builtin_amdgcn_wave_barrier(); __builtin_amdgcn_fence(__ATOMIC_ACQUIRE, "wavefront");
;     { const int n8 = lane >> 3, k8 = (lane & 7) * 8;
; #pragma unroll
;       for (int i = 0; i < 8; ++i) { const int n = 8 * i + n8; const float* sp = T + k8 * 65 + n;
;           u32x4 o; o.x = cvt_pk_bf16(sp[0], sp[65]); o.y = cvt_pk_bf16(sp[2 * 65], sp[3 * 65]); o.z = cvt_pk_bf16(sp[4 * 65], sp[5 * 65]); o.w = cvt_pk_bf16(sp[6 * 65], sp[7 * 65]);
;           *(u32x4*)(WT + (size_t)(n0 + n) * K + k0 + k8) = o; } }
;     __builtin_amdgcn_fence(__ATOMIC_RELEASE, "wavefront"); __builtin_amdgcn_wave_barrier(); __builtin_amdgcn_fence(__ATOMIC_ACQUIRE, "wavefront");
	ds_write2_b32 v60, v116, v117 offset1:1
	v_add_u32_e32 v60, 0x1048, v4
	ds_write2_b32 v60, v118, v119 offset1:1
	v_add_u32_e32 v60, 0x1450, v4
	v_add_u32_e32 v4, 0x1458, v4
	s_waitcnt vmcnt(0)
	ds_write2_b32 v4, v122, v123 offset1:1
	v_lshlrev_b32_e32 v4, 1, v59
	v_add_u32_e32 v59, 0x400, v48
	v_lshl_add_u64 v[80:81], v[14:15], 0, v[4:5]
	v_or_b32_e32 v4, v124, v47
	ds_write2_b32 v60, v120, v121 offset1:1
	ds_read2_b32 v[64:65], v48 offset0:65 offset1:73
	ds_read2_b32 v[66:67], v48 offset1:8
	ds_read2_b32 v[68:69], v48 offset0:130 offset1:138
	ds_read2_b32 v[70:71], v48 offset0:195 offset1:203
	ds_read2_b32 v[72:73], v59 offset0:4 offset1:12
	ds_read2_b32 v[74:75], v59 offset0:69 offset1:77
	ds_read2_b32 v[76:77], v59 offset0:134 offset1:142
	ds_read2_b32 v[78:79], v59 offset0:199 offset1:207
	v_mul_u32_u24_e32 v4, 0x1600, v4
	v_lshlrev_b32_e32 v4, 1, v4
	v_lshl_add_u64 v[82:83], v[80:81], 0, v[4:5]
	v_or_b32_e32 v4, v124, v49
	v_mul_u32_u24_e32 v4, 0x1600, v4
	s_waitcnt lgkmcnt(6)
	v_cvt_pk_bf16_f32 v60, v66, v64
	v_lshlrev_b32_e32 v4, 1, v4
	s_waitcnt lgkmcnt(4)
	v_cvt_pk_bf16_f32 v61, v68, v70
	s_waitcnt lgkmcnt(2)
	v_cvt_pk_bf16_f32 v62, v72, v74
	s_waitcnt lgkmcnt(0)
	v_cvt_pk_bf16_f32 v63, v76, v78
	global_store_dwordx4 v[82:83], v[60:63], off
	s_nop 1
	v_cvt_pk_bf16_f32 v60, v67, v65
	v_lshl_add_u64 v[64:65], v[80:81], 0, v[4:5]
	v_or_b32_e32 v4, v124, v50
	v_cvt_pk_bf16_f32 v61, v69, v71
	v_cvt_pk_bf16_f32 v62, v73, v75
	v_cvt_pk_bf16_f32 v63, v77, v79
	ds_read2_b32 v[66:67], v48 offset0:16 offset1:24
	ds_read2_b32 v[68:69], v48 offset0:81 offset1:89
	ds_read2_b32 v[70:71], v48 offset0:146 offset1:154
	ds_read2_b32 v[72:73], v48 offset0:211 offset1:219
	ds_read2_b32 v[74:75], v59 offset0:20 offset1:28
	ds_read2_b32 v[76:77], v59 offset0:85 offset1:93
	ds_read2_b32 v[78:79], v59 offset0:150 offset1:158
	ds_read2_b32 v[82:83], v59 offset0:215 offset1:223
	v_mul_u32_u24_e32 v4, 0x1600, v4
	v_lshlrev_b32_e32 v4, 1, v4
	global_store_dwordx4 v[64:65], v[60:63], off
	v_lshl_add_u64 v[64:65], v[80:81], 0, v[4:5]
	v_or_b32_e32 v4, v124, v51
	v_mul_u32_u24_e32 v4, 0x1600, v4
	v_lshlrev_b32_e32 v4, 1, v4
	s_waitcnt lgkmcnt(6)
	v_cvt_pk_bf16_f32 v60, v66, v68
	s_waitcnt lgkmcnt(4)
	v_cvt_pk_bf16_f32 v61, v70, v72
	s_waitcnt lgkmcnt(2)
	v_cvt_pk_bf16_f32 v62, v74, v76
	s_waitcnt lgkmcnt(0)
	v_cvt_pk_bf16_f32 v63, v78, v82
	global_store_dwordx4 v[64:65], v[60:63], off
	v_lshl_add_u64 v[64:65], v[80:81], 0, v[4:5]
	v_or_b32_e32 v4, v124, v52
	v_cvt_pk_bf16_f32 v60, v67, v69
	v_cvt_pk_bf16_f32 v61, v71, v73
	v_cvt_pk_bf16_f32 v62, v75, v77
	v_cvt_pk_bf16_f32 v63, v79, v83
	ds_read2_b32 v[66:67], v48 offset0:32 offset1:40
	ds_read2_b32 v[68:69], v48 offset0:97 offset1:105
	ds_read2_b32 v[70:71], v48 offset0:162 offset1:170
	ds_read2_b32 v[72:73], v48 offset0:227 offset1:235
	ds_read2_b32 v[74:75], v59 offset0:36 offset1:44
	ds_read2_b32 v[76:77], v59 offset0:101 offset1:109
	ds_read2_b32 v[78:79], v59 offset0:166 offset1:174
	ds_read2_b32 v[82:83], v59 offset0:231 offset1:239
	v_mul_u32_u24_e32 v4, 0x1600, v4
	v_lshlrev_b32_e32 v4, 1, v4
	global_store_dwordx4 v[64:65], v[60:63], off
	v_lshl_add_u64 v[64:65], v[80:81], 0, v[4:5]
	v_or_b32_e32 v4, v124, v53
	v_mul_u32_u24_e32 v4, 0x1600, v4
	v_lshlrev_b32_e32 v4, 1, v4
	s_waitcnt lgkmcnt(6)
	v_cvt_pk_bf16_f32 v60, v66, v68
	s_waitcnt lgkmcnt(4)
	v_cvt_pk_bf16_f32 v61, v70, v72
	s_waitcnt lgkmcnt(2)
	v_cvt_pk_bf16_f32 v62, v74, v76
	s_waitcnt lgkmcnt(0)
	v_cvt_pk_bf16_f32 v63, v78, v82
	global_store_dwordx4 v[64:65], v[60:63], off
	v_lshl_add_u64 v[64:65], v[80:81], 0, v[4:5]
	v_or_b32_e32 v4, v124, v54
	v_cvt_pk_bf16_f32 v60, v67, v69
	v_cvt_pk_bf16_f32 v61, v71, v73
	v_cvt_pk_bf16_f32 v62, v75, v77
	v_cvt_pk_bf16_f32 v63, v79, v83
	ds_read2_b32 v[66:67], v48 offset0:48 offset1:56
	ds_read2_b32 v[68:69], v48 offset0:113 offset1:121
	ds_read2_b32 v[70:71], v48 offset0:178 offset1:186
	ds_read2_b32 v[72:73], v48 offset0:243 offset1:251
	ds_read2_b32 v[74:75], v59 offset0:52 offset1:60
	ds_read2_b32 v[76:77], v59 offset0:117 offset1:125
	ds_read2_b32 v[78:79], v59 offset0:182 offset1:190
	ds_read2_b32 v[82:83], v59 offset0:247 offset1:255
	v_mul_u32_u24_e32 v4, 0x1600, v4
	v_lshlrev_b32_e32 v4, 1, v4
	global_store_dwordx4 v[64:65], v[60:63], off
	v_lshl_add_u64 v[64:65], v[80:81], 0, v[4:5]
	v_or_b32_e32 v4, v124, v55
	v_mul_u32_u24_e32 v4, 0x1600, v4
	v_lshlrev_b32_e32 v4, 1, v4
	s_waitcnt lgkmcnt(6)
	v_cvt_pk_bf16_f32 v60, v66, v68
	s_waitcnt lgkmcnt(4)
	v_cvt_pk_bf16_f32 v61, v70, v72
	s_waitcnt lgkmcnt(2)
	v_cvt_pk_bf16_f32 v62, v74, v76
	s_waitcnt lgkmcnt(0)
	v_cvt_pk_bf16_f32 v63, v78, v82
	global_store_dwordx4 v[64:65], v[60:63], off
	v_lshl_add_u64 v[64:65], v[80:81], 0, v[4:5]
	s_nop 0
	v_cvt_pk_bf16_f32 v60, v67, v69
	v_cvt_pk_bf16_f32 v61, v71, v73
	v_cvt_pk_bf16_f32 v62, v75, v77
	v_cvt_pk_bf16_f32 v63, v79, v83
	global_store_dwordx4 v[64:65], v[60:63], off

; __device__ __forceinline__ void convT_tile(const float* __restrict__ W, int K, int N, bf16_t* __restrict__ WT, int tile, unsigned char* shm, int wave, int lane) {
;     const int ntn = N / 64, k0 = (tile / ntn) * 64, n0 = (tile % ntn) * 64;
;     float* T = (float*)shm + wave * (64 * 65);
;     { const int r4 = lane >> 4, c4 = (lane & 15) * 4;
; #pragma unroll
;       for (int i = 0; i < 16; ++i) { const int rr = 4 * i + r4; const float4 v = *(const float4*)(W + (size_t)(k0 + rr) * N + n0 + c4);
;           T[rr * 65 + c4] = v.x; T[rr * 65 + c4 + 1] = v.y; T[rr * 65 + c4 + 2] = v.z; T[rr * 65 + c4 + 3] = v.w; } }
; __device__ __forceinline__ void phase_lprep(PRef p, int layer, unsigned char* shm, const float* hL_, const float* hC_) {
;     ...
;         if (r < T_UP) { convT_tile(p.in[30] + (size_t)layer * 2048 * 11264, 2048, 11264, (bf16_t*)(p.ws + O_WT_UP), r, shm, wave, lane); continue; } r -= T_UP;
.LBB0_757:
	s_andn2_saveexec_b64 s[18:19], s[18:19]
	s_cbranch_execz .LBB0_759
	v_add_u16_e32 v4, 0xf200, v58
	v_mul_u32_u24_e32 v59, 0xba2f, v4
	v_lshrrev_b32_e32 v59, 23, v59
	v_lshlrev_b16_e32 v124, 6, v59
	v_mul_lo_u16_e32 v59, 0xb0, v59
	v_sub_u16_e32 v4, v4, v59
	v_lshlrev_b16_e32 v59, 6, v4
	v_lshlrev_b32_e32 v4, 2, v59
	v_lshl_add_u64 v[120:121], v[16:17], 0, v[4:5]
	v_or_b32_e32 v4, v1, v124
	v_mul_u32_u24_e32 v4, 0x2c00, v4
	v_lshlrev_b32_e32 v4, 2, v4
	v_lshl_add_u64 v[60:61], v[120:121], 0, v[4:5]
	v_or_b32_e32 v4, v29, v124
	v_mul_u32_u24_e32 v4, 0x2c00, v4
	v_lshlrev_b32_e32 v4, 2, v4
	v_lshl_add_u64 v[64:65], v[120:121], 0, v[4:5]
	v_or_b32_e32 v4, v31, v124
	v_mul_u32_u24_e32 v4, 0x2c00, v4
	v_lshlrev_b32_e32 v4, 2, v4
	v_lshl_add_u64 v[68:69], v[120:121], 0, v[4:5]
	v_or_b32_e32 v4, v32, v124
	v_mul_u32_u24_e32 v4, 0x2c00, v4
	v_lshlrev_b32_e32 v4, 2, v4
	v_lshl_add_u64 v[72:73], v[120:121], 0, v[4:5]
	v_or_b32_e32 v4, v33, v124
	v_mul_u32_u24_e32 v4, 0x2c00, v4
	v_lshlrev_b32_e32 v4, 2, v4
	v_lshl_add_u64 v[76:77], v[120:121], 0, v[4:5]
	v_or_b32_e32 v4, v34, v124
	v_mul_u32_u24_e32 v4, 0x2c00, v4
	v_lshlrev_b32_e32 v4, 2, v4
	v_lshl_add_u64 v[80:81], v[120:121], 0, v[4:5]
	v_or_b32_e32 v4, v36, v124
	v_mul_u32_u24_e32 v4, 0x2c00, v4
	v_lshlrev_b32_e32 v4, 2, v4
	v_lshl_add_u64 v[84:85], v[120:121], 0, v[4:5]
	v_or_b32_e32 v4, v37, v124
	v_mul_u32_u24_e32 v4, 0x2c00, v4
	global_load_dwordx4 v[60:63], v[60:61], off nt
	s_nop 0
	global_load_dwordx4 v[64:67], v[64:65], off nt
	v_lshlrev_b32_e32 v4, 2, v4
	v_lshl_add_u64 v[88:89], v[120:121], 0, v[4:5]
	v_or_b32_e32 v4, v38, v124
	v_mul_u32_u24_e32 v4, 0x2c00, v4
	global_load_dwordx4 v[68:71], v[68:69], off nt
	s_nop 0
	global_load_dwordx4 v[72:75], v[72:73], off nt
	v_lshlrev_b32_e32 v4, 2, v4
	v_lshl_add_u64 v[92:93], v[120:121], 0, v[4:5]
	v_or_b32_e32 v4, v39, v124
	v_mul_u32_u24_e32 v4, 0x2c00, v4
	v_lshlrev_b32_e32 v4, 2, v4
	global_load_dwordx4 v[76:79], v[76:77], off nt
	s_nop 0
	global_load_dwordx4 v[80:83], v[80:81], off nt
	v_lshl_add_u64 v[96:97], v[120:121], 0, v[4:5]
	v_or_b32_e32 v4, v40, v124
	v_mul_u32_u24_e32 v4, 0x2c00, v4
	v_lshlrev_b32_e32 v4, 2, v4
	global_load_dwordx4 v[84:87], v[84:85], off nt
	s_nop 0
	global_load_dwordx4 v[88:91], v[88:89], off nt
	v_lshl_add_u64 v[100:101], v[120:121], 0, v[4:5]
	v_or_b32_e32 v4, v42, v124
	v_mul_u32_u24_e32 v4, 0x2c00, v4
	v_lshlrev_b32_e32 v4, 2, v4
	v_lshl_add_u64 v[104:105], v[120:121], 0, v[4:5]
	v_or_b32_e32 v4, v43, v124
	global_load_dwordx4 v[92:95], v[92:93], off nt
	s_nop 0
	global_load_dwordx4 v[96:99], v[96:97], off nt
	v_mul_u32_u24_e32 v4, 0x2c00, v4
	v_lshlrev_b32_e32 v4, 2, v4
	v_lshl_add_u64 v[108:109], v[120:121], 0, v[4:5]
	v_or_b32_e32 v4, v44, v124
	global_load_dwordx4 v[100:103], v[100:101], off nt
	s_nop 0
	global_load_dwordx4 v[104:107], v[104:105], off nt
	v_mul_u32_u24_e32 v4, 0x2c00, v4
	v_lshlrev_b32_e32 v4, 2, v4
	v_lshl_add_u64 v[112:113], v[120:121], 0, v[4:5]
	v_or_b32_e32 v4, v45, v124
	global_load_dwordx4 v[108:111], v[108:109], off nt
	v_mul_u32_u24_e32 v4, 0x2c00, v4
	v_lshlrev_b32_e32 v4, 2, v4
	global_load_dwordx4 v[112:115], v[112:113], off nt
	v_lshl_add_u64 v[116:117], v[120:121], 0, v[4:5]
	v_or_b32_e32 v4, v46, v124
	v_mul_u32_u24_e32 v4, 0x2c00, v4
	global_load_dwordx4 v[116:119], v[116:117], off nt
	v_lshlrev_b32_e32 v4, 2, v4
	v_lshl_add_u64 v[120:121], v[120:121], 0, v[4:5]
	global_load_dwordx4 v[120:123], v[120:121], off nt
	v_add_u32_e32 v4, v3, v27
	s_waitcnt vmcnt(15)
	ds_write2_b32 v4, v60, v61 offset1:1
	ds_write2_b32 v4, v62, v63 offset0:2 offset1:3
	v_add_u32_e32 v60, 0x410, v4
	s_waitcnt vmcnt(14)
	ds_write2_b32 v60, v64, v65 offset1:1
	v_add_u32_e32 v60, 0x418, v4
	ds_write2_b32 v60, v66, v67 offset1:1
	v_add_u32_e32 v60, 0x820, v4
	s_waitcnt vmcnt(13)
	ds_write2_b32 v60, v68, v69 offset1:1
	v_add_u32_e32 v60, 0x828, v4
	ds_write2_b32 v60, v70, v71 offset1:1
	v_add_u32_e32 v60, 0xc30, v4
	s_waitcnt vmcnt(12)
	ds_write2_b32 v60, v72, v73 offset1:1
	v_add_u32_e32 v60, 0xc38, v4
	ds_write2_b32 v60, v74, v75 offset1:1
	v_add_u32_e32 v60, 0x1040, v4
	s_waitcnt vmcnt(11)
	ds_write2_b32 v60, v76, v77 offset1:1
	v_add_u32_e32 v60, 0x1048, v4
	v_add_u32_e32 v4, 0x1450, v4
	s_waitcnt vmcnt(10)
	ds_write2_b32 v4, v80, v81 offset1:1
	v_add_u32_e32 v4, v3, v35
	ds_write2_b32 v60, v78, v79 offset1:1
	v_add_u32_e32 v60, 0x410, v4
	s_waitcnt vmcnt(9)
	ds_write2_b32 v60, v84, v85 offset1:1
	v_add_u32_e32 v60, 0x418, v4
	ds_write2_b32 v60, v86, v87 offset1:1
	v_add_u32_e32 v60, 0x820, v4
	s_waitcnt vmcnt(8)
	ds_write2_b32 v60, v88, v89 offset1:1
	v_add_u32_e32 v60, 0x828, v4
	ds_write2_b32 v60, v90, v91 offset1:1
	v_add_u32_e32 v60, 0xc30, v4
	s_waitcnt vmcnt(7)
	ds_write2_b32 v60, v92, v93 offset1:1
	v_add_u32_e32 v60, 0xc38, v4
	ds_write2_b32 v60, v94, v95 offset1:1
	v_add_u32_e32 v60, 0x1040, v4
	ds_write2_b32 v4, v82, v83 offset0:2 offset1:3
	s_waitcnt vmcnt(6)
	ds_write2_b32 v60, v96, v97 offset1:1
	v_add_u32_e32 v60, 0x1048, v4
	v_add_u32_e32 v4, 0x1450, v4
	s_waitcnt vmcnt(5)
	ds_write2_b32 v4, v100, v101 offset1:1
	v_add_u32_e32 v4, v3, v41
	ds_write2_b32 v60, v98, v99 offset1:1
	v_add_u32_e32 v60, 0x410, v4
	s_waitcnt vmcnt(4)
; __device__ __forceinline__ unsigned cvt_pk_bf16(float lo, float hi) { unsigned r; asm("v_cvt_pk_bf16_f32 %0, %1, %2" : "=v"(r) : "v"(lo), "v"(hi)); return r; }
; __device__ __forceinline__ void convT_tile(const float* __restrict__ W, int K, int N, bf16_t* __restrict__ WT, int tile, unsigned char* shm, int wave, int lane) {
;     ...
;     __builtin_amdgcn_fence(__ATOMIC_RELEASE, "wavefront"); __builtin_amdgcn_wave_barrier(); __builtin_amdgcn_fence(__ATOMIC_ACQUIRE, "wavefront");
;     { const int n8 = lane >> 3, k8 = (lane & 7) * 8;
; #pragma unroll
;       for (int i = 0; i < 8; ++i) { const int n = 8 * i + n8; const float* sp = T + k8 * 65 + n;
;           u32x4 o; o.x = cvt_pk_bf16(sp[0], sp[65]); o.y = cvt_pk_bf16(sp[2 * 65], sp[3 * 65]); o.z = cvt_pk_bf16(sp[4 * 65], sp[5 * 65]); o.w = cvt_pk_bf16(sp[6 * 65], sp[7 * 65]);
;           *(u32x4*)(WT + (size_t)(n0 + n) * K + k0 + k8) = o; } }
;     __builtin_amdgcn_fence(__ATOMIC_RELEASE, "wavefront"); __builtin_amdgcn_wave_barrier(); __builtin_amdgcn_fence(__ATOMIC_ACQUIRE, "wavefront");
	ds_write2_b32 v60, v104, v105 offset1:1
	v_add_u32_e32 v60, 0x418, v4
	ds_write2_b32 v60, v106, v107 offset1:1
	v_add_u32_e32 v60, 0x820, v4
	s_waitcnt vmcnt(3)
	ds_write2_b32 v60, v108, v109 offset1:1
	v_add_u32_e32 v60, 0x828, v4
	ds_write2_b32 v60, v110, v111 offset1:1
	v_add_u32_e32 v60, 0xc30, v4
	s_waitcnt vmcnt(2)
	ds_write2_b32 v60, v112, v113 offset1:1
	v_add_u32_e32 v60, 0xc38, v4
	ds_write2_b32 v60, v114, v115 offset1:1
	v_add_u32_e32 v60, 0x1040, v4
	s_waitcnt vmcnt(1)
	ds_write2_b32 v60, v116, v117 offset1:1
	v_add_u32_e32 v60, 0x1048, v4
	ds_write2_b32 v4, v102, v103 offset0:2 offset1:3
	ds_write2_b32 v60, v118, v119 offset1:1
	v_add_u32_e32 v60, 0x1450, v4
	v_add_u32_e32 v4, 0x1458, v4
	v_add_u32_e32 v84, 0x400, v48
	s_waitcnt vmcnt(0)
	ds_write2_b32 v60, v120, v121 offset1:1
	ds_write2_b32 v4, v122, v123 offset1:1
	ds_read2_b32 v[64:65], v48 offset0:65 offset1:73
	ds_read2_b32 v[66:67], v48 offset1:8
	ds_read2_b32 v[68:69], v48 offset0:130 offset1:138
	ds_read2_b32 v[70:71], v48 offset0:195 offset1:203
	ds_read2_b32 v[72:73], v84 offset0:4 offset1:12
	ds_read2_b32 v[74:75], v84 offset0:69 offset1:77
	ds_read2_b32 v[76:77], v84 offset0:134 offset1:142
	ds_read2_b32 v[78:79], v84 offset0:199 offset1:207
	v_lshlrev_b32_e32 v4, 1, v124
	v_lshl_add_u64 v[80:81], v[18:19], 0, v[4:5]
	v_or_b32_e32 v4, v47, v59
	v_lshlrev_b32_e32 v4, 12, v4
	v_lshl_add_u64 v[82:83], v[80:81], 0, v[4:5]
	s_waitcnt lgkmcnt(6)
	v_cvt_pk_bf16_f32 v60, v66, v64
	s_waitcnt lgkmcnt(4)
	v_cvt_pk_bf16_f32 v61, v68, v70
	s_waitcnt lgkmcnt(2)
	v_cvt_pk_bf16_f32 v62, v72, v74
	s_waitcnt lgkmcnt(0)
	v_cvt_pk_bf16_f32 v63, v76, v78
	global_store_dwordx4 v[82:83], v[60:63], off
	v_or_b32_e32 v4, v49, v59
	v_lshlrev_b32_e32 v4, 12, v4
	v_cvt_pk_bf16_f32 v60, v67, v65
	v_cvt_pk_bf16_f32 v61, v69, v71
	v_cvt_pk_bf16_f32 v62, v73, v75
	v_cvt_pk_bf16_f32 v63, v77, v79
	ds_read2_b32 v[66:67], v48 offset0:16 offset1:24
	ds_read2_b32 v[68:69], v48 offset0:81 offset1:89
	ds_read2_b32 v[70:71], v48 offset0:146 offset1:154
	ds_read2_b32 v[72:73], v48 offset0:211 offset1:219
	ds_read2_b32 v[74:75], v84 offset0:20 offset1:28
	ds_read2_b32 v[76:77], v84 offset0:85 offset1:93
	ds_read2_b32 v[78:79], v84 offset0:150 offset1:158
	ds_read2_b32 v[82:83], v84 offset0:215 offset1:223
	v_lshl_add_u64 v[64:65], v[80:81], 0, v[4:5]
	v_or_b32_e32 v4, v50, v59
	v_lshlrev_b32_e32 v4, 12, v4
	global_store_dwordx4 v[64:65], v[60:63], off
	v_lshl_add_u64 v[64:65], v[80:81], 0, v[4:5]
	v_or_b32_e32 v4, v51, v59
	s_waitcnt lgkmcnt(6)
	v_cvt_pk_bf16_f32 v60, v66, v68
	s_waitcnt lgkmcnt(4)
	v_cvt_pk_bf16_f32 v61, v70, v72
	s_waitcnt lgkmcnt(2)
	v_cvt_pk_bf16_f32 v62, v74, v76
	s_waitcnt lgkmcnt(0)
	v_cvt_pk_bf16_f32 v63, v78, v82
	global_store_dwordx4 v[64:65], v[60:63], off
	v_lshlrev_b32_e32 v4, 12, v4
	v_lshl_add_u64 v[64:65], v[80:81], 0, v[4:5]
	v_cvt_pk_bf16_f32 v60, v67, v69
	v_cvt_pk_bf16_f32 v61, v71, v73
	v_cvt_pk_bf16_f32 v62, v75, v77
	v_cvt_pk_bf16_f32 v63, v79, v83
	ds_read2_b32 v[66:67], v48 offset0:32 offset1:40
	ds_read2_b32 v[68:69], v48 offset0:97 offset1:105
	ds_read2_b32 v[70:71], v48 offset0:162 offset1:170
	ds_read2_b32 v[72:73], v48 offset0:227 offset1:235
	ds_read2_b32 v[74:75], v84 offset0:36 offset1:44
	ds_read2_b32 v[76:77], v84 offset0:101 offset1:109
	ds_read2_b32 v[78:79], v84 offset0:166 offset1:174
	ds_read2_b32 v[82:83], v84 offset0:231 offset1:239
	v_or_b32_e32 v4, v52, v59
	v_lshlrev_b32_e32 v4, 12, v4
	global_store_dwordx4 v[64:65], v[60:63], off
	v_lshl_add_u64 v[64:65], v[80:81], 0, v[4:5]
	v_or_b32_e32 v4, v53, v59
	s_waitcnt lgkmcnt(6)
	v_cvt_pk_bf16_f32 v60, v66, v68
	s_waitcnt lgkmcnt(4)
	v_cvt_pk_bf16_f32 v61, v70, v72
	s_waitcnt lgkmcnt(2)
	v_cvt_pk_bf16_f32 v62, v74, v76
	s_waitcnt lgkmcnt(0)
	v_cvt_pk_bf16_f32 v63, v78, v82
	global_store_dwordx4 v[64:65], v[60:63], off
	v_lshlrev_b32_e32 v4, 12, v4
	v_lshl_add_u64 v[64:65], v[80:81], 0, v[4:5]
	v_cvt_pk_bf16_f32 v60, v67, v69
	v_cvt_pk_bf16_f32 v61, v71, v73
	v_cvt_pk_bf16_f32 v62, v75, v77
	v_cvt_pk_bf16_f32 v63, v79, v83
	ds_read2_b32 v[66:67], v48 offset0:48 offset1:56
	ds_read2_b32 v[68:69], v48 offset0:113 offset1:121
	ds_read2_b32 v[70:71], v48 offset0:178 offset1:186
	ds_read2_b32 v[72:73], v48 offset0:243 offset1:251
	ds_read2_b32 v[74:75], v84 offset0:52 offset1:60
	ds_read2_b32 v[76:77], v84 offset0:117 offset1:125
	ds_read2_b32 v[78:79], v84 offset0:182 offset1:190
	ds_read2_b32 v[82:83], v84 offset0:247 offset1:255
	v_or_b32_e32 v4, v54, v59
	v_lshlrev_b32_e32 v4, 12, v4
	global_store_dwordx4 v[64:65], v[60:63], off
	v_lshl_add_u64 v[64:65], v[80:81], 0, v[4:5]
	v_or_b32_e32 v4, v55, v59
	v_lshlrev_b32_e32 v4, 12, v4
	s_waitcnt lgkmcnt(6)
	v_cvt_pk_bf16_f32 v60, v66, v68
	s_waitcnt lgkmcnt(4)
	v_cvt_pk_bf16_f32 v61, v70, v72
	s_waitcnt lgkmcnt(2)
	v_cvt_pk_bf16_f32 v62, v74, v76
	s_waitcnt lgkmcnt(0)
	v_cvt_pk_bf16_f32 v63, v78, v82
	global_store_dwordx4 v[64:65], v[60:63], off
	v_lshl_add_u64 v[64:65], v[80:81], 0, v[4:5]
	s_nop 0
	v_cvt_pk_bf16_f32 v60, v67, v69
	v_cvt_pk_bf16_f32 v61, v71, v73
	v_cvt_pk_bf16_f32 v62, v75, v77
	v_cvt_pk_bf16_f32 v63, v79, v83
	global_store_dwordx4 v[64:65], v[60:63], off

; __device__ __forceinline__ void convT_tile(const float* __restrict__ W, int K, int N, bf16_t* __restrict__ WT, int tile, unsigned char* shm, int wave, int lane) {
;     const int ntn = N / 64, k0 = (tile / ntn) * 64, n0 = (tile % ntn) * 64;
;     float* T = (float*)shm + wave * (64 * 65);
;     { const int r4 = lane >> 4, c4 = (lane & 15) * 4;
; #pragma unroll
;       for (int i = 0; i < 16; ++i) { const int rr = 4 * i + r4; const float4 v = *(const float4*)(W + (size_t)(k0 + rr) * N + n0 + c4);
;           T[rr * 65 + c4] = v.x; T[rr * 65 + c4 + 1] = v.y; T[rr * 65 + c4 + 2] = v.z; T[rr * 65 + c4 + 3] = v.w; } }
; __device__ __forceinline__ void phase_lprep(PRef p, int layer, unsigned char* shm, const float* hL_, const float* hC_) {
;     ...
;         if (r < T_OUT) { convT_tile(p.in[28] + (size_t)layer * 2048 * 2048, 2048, 2048, (bf16_t*)(p.ws + O_WT_OUT), r, shm, wave, lane); continue; } r -= T_OUT;
.LBB0_760:
	s_andn2_saveexec_b64 s[16:17], s[16:17]
	s_cbranch_execz .LBB0_762
	v_add_u32_e32 v4, 0x3400, v56
	v_and_b32_e32 v124, 0x7c0, v26
	v_and_b32_e32 v59, 0x1ffc0, v4
	v_lshlrev_b32_e32 v4, 2, v124
	v_lshl_add_u64 v[120:121], v[20:21], 0, v[4:5]
	v_or_b32_e32 v4, v59, v1
	v_lshlrev_b32_e32 v4, 13, v4
	v_lshl_add_u64 v[60:61], v[120:121], 0, v[4:5]
	v_or_b32_e32 v4, v59, v29
	v_lshlrev_b32_e32 v4, 13, v4
	v_lshl_add_u64 v[64:65], v[120:121], 0, v[4:5]
	v_or_b32_e32 v4, v59, v31
	v_lshlrev_b32_e32 v4, 13, v4
	v_lshl_add_u64 v[68:69], v[120:121], 0, v[4:5]
	v_or_b32_e32 v4, v59, v32
	v_lshlrev_b32_e32 v4, 13, v4
	v_lshl_add_u64 v[72:73], v[120:121], 0, v[4:5]
	v_or_b32_e32 v4, v59, v33
	v_lshlrev_b32_e32 v4, 13, v4
	v_lshl_add_u64 v[76:77], v[120:121], 0, v[4:5]
	v_or_b32_e32 v4, v59, v34
	v_lshlrev_b32_e32 v4, 13, v4
	v_lshl_add_u64 v[80:81], v[120:121], 0, v[4:5]
	v_or_b32_e32 v4, v59, v36
	v_lshlrev_b32_e32 v4, 13, v4
	global_load_dwordx4 v[60:63], v[60:61], off nt
	s_nop 0
	global_load_dwordx4 v[64:67], v[64:65], off nt
	s_nop 0
	global_load_dwordx4 v[68:71], v[68:69], off nt
	s_nop 0
	global_load_dwordx4 v[72:75], v[72:73], off nt
	s_nop 0
	global_load_dwordx4 v[76:79], v[76:77], off nt
	s_nop 0
	global_load_dwordx4 v[80:83], v[80:81], off nt
	v_lshl_add_u64 v[84:85], v[120:121], 0, v[4:5]
	v_or_b32_e32 v4, v59, v37
	global_load_dwordx4 v[84:87], v[84:85], off nt
	v_lshlrev_b32_e32 v4, 13, v4
	v_lshl_add_u64 v[88:89], v[120:121], 0, v[4:5]
	v_or_b32_e32 v4, v59, v38
	global_load_dwordx4 v[88:91], v[88:89], off nt
	v_lshlrev_b32_e32 v4, 13, v4
	v_lshl_add_u64 v[92:93], v[120:121], 0, v[4:5]
	v_or_b32_e32 v4, v59, v39
	global_load_dwordx4 v[92:95], v[92:93], off nt
	v_lshlrev_b32_e32 v4, 13, v4
	v_lshl_add_u64 v[96:97], v[120:121], 0, v[4:5]
	v_or_b32_e32 v4, v59, v40
	global_load_dwordx4 v[96:99], v[96:97], off nt
	v_lshlrev_b32_e32 v4, 13, v4
	v_lshl_add_u64 v[100:101], v[120:121], 0, v[4:5]
	v_or_b32_e32 v4, v59, v42
	global_load_dwordx4 v[100:103], v[100:101], off nt
	v_lshlrev_b32_e32 v4, 13, v4
	v_lshl_add_u64 v[104:105], v[120:121], 0, v[4:5]
	v_or_b32_e32 v4, v59, v43
	global_load_dwordx4 v[104:107], v[104:105], off nt
	v_lshlrev_b32_e32 v4, 13, v4
	v_lshl_add_u64 v[108:109], v[120:121], 0, v[4:5]
	v_or_b32_e32 v4, v59, v44
	global_load_dwordx4 v[108:111], v[108:109], off nt
	v_lshlrev_b32_e32 v4, 13, v4
	v_lshl_add_u64 v[112:113], v[120:121], 0, v[4:5]
	v_or_b32_e32 v4, v59, v45
	global_load_dwordx4 v[112:115], v[112:113], off nt
	v_lshlrev_b32_e32 v4, 13, v4
	v_lshl_add_u64 v[116:117], v[120:121], 0, v[4:5]
	v_or_b32_e32 v4, v59, v46
	global_load_dwordx4 v[116:119], v[116:117], off nt
	v_lshlrev_b32_e32 v4, 13, v4
	v_lshl_add_u64 v[120:121], v[120:121], 0, v[4:5]
	global_load_dwordx4 v[120:123], v[120:121], off nt
	v_add_u32_e32 v4, v3, v27
	v_add_u32_e32 v125, v3, v35
	v_add_u32_e32 v126, 0x410, v4
	v_add_u32_e32 v127, 0x418, v4
	v_add_u32_e32 v128, 0x820, v4
	v_add_u32_e32 v129, 0x828, v4
	v_add_u32_e32 v130, 0xc30, v4
	v_add_u32_e32 v131, 0xc38, v4
	v_add_u32_e32 v132, 0x1040, v4
	v_add_u32_e32 v133, 0x1048, v4
	v_add_u32_e32 v134, 0x1450, v4
	s_waitcnt vmcnt(15)
	ds_write2_b32 v4, v60, v61 offset1:1
	ds_write2_b32 v4, v62, v63 offset0:2 offset1:3
	s_waitcnt vmcnt(14)
	ds_write2_b32 v126, v64, v65 offset1:1
	ds_write2_b32 v127, v66, v67 offset1:1
	s_waitcnt vmcnt(13)
	ds_write2_b32 v128, v68, v69 offset1:1
	ds_write2_b32 v129, v70, v71 offset1:1
	s_waitcnt vmcnt(12)
	ds_write2_b32 v130, v72, v73 offset1:1
	ds_write2_b32 v131, v74, v75 offset1:1
	s_waitcnt vmcnt(11)
	ds_write2_b32 v132, v76, v77 offset1:1
	ds_write2_b32 v133, v78, v79 offset1:1
	s_waitcnt vmcnt(10)
	ds_write2_b32 v134, v80, v81 offset1:1
	ds_write2_b32 v125, v82, v83 offset0:2 offset1:3
	v_add_u32_e32 v4, 0x410, v125
	s_waitcnt vmcnt(9)
	ds_write2_b32 v4, v84, v85 offset1:1
	v_add_u32_e32 v4, 0x418, v125
	ds_write2_b32 v4, v86, v87 offset1:1
	v_add_u32_e32 v4, 0x820, v125
	s_waitcnt vmcnt(8)
	ds_write2_b32 v4, v88, v89 offset1:1
	v_add_u32_e32 v4, 0x828, v125
	ds_write2_b32 v4, v90, v91 offset1:1
	v_add_u32_e32 v4, 0xc30, v125
	s_waitcnt vmcnt(7)
	ds_write2_b32 v4, v92, v93 offset1:1
	v_add_u32_e32 v4, 0xc38, v125
	ds_write2_b32 v4, v94, v95 offset1:1
	v_add_u32_e32 v4, 0x1040, v125
	s_waitcnt vmcnt(6)
	ds_write2_b32 v4, v96, v97 offset1:1
	v_add_u32_e32 v4, 0x1048, v125
	ds_write2_b32 v4, v98, v99 offset1:1
	v_add_u32_e32 v4, 0x1450, v125
	s_waitcnt vmcnt(5)
	ds_write2_b32 v4, v100, v101 offset1:1
	v_add_u32_e32 v4, v3, v41
	v_add_u32_e32 v60, 0x410, v4
	ds_write2_b32 v4, v102, v103 offset0:2 offset1:3
	s_waitcnt vmcnt(4)
	ds_write2_b32 v60, v104, v105 offset1:1
	v_add_u32_e32 v60, 0x418, v4
	ds_write2_b32 v60, v106, v107 offset1:1
	v_add_u32_e32 v60, 0x820, v4
	s_waitcnt vmcnt(3)
	ds_write2_b32 v60, v108, v109 offset1:1
	v_add_u32_e32 v60, 0x828, v4
	ds_write2_b32 v60, v110, v111 offset1:1
	v_add_u32_e32 v60, 0xc30, v4
	s_waitcnt vmcnt(2)
; __device__ __forceinline__ unsigned cvt_pk_bf16(float lo, float hi) { unsigned r; asm("v_cvt_pk_bf16_f32 %0, %1, %2" : "=v"(r) : "v"(lo), "v"(hi)); return r; }
; __device__ __forceinline__ void convT_tile(const float* __restrict__ W, int K, int N, bf16_t* __restrict__ WT, int tile, unsigned char* shm, int wave, int lane) {
;     ...
;     __builtin_amdgcn_fence(__ATOMIC_RELEASE, "wavefront"); __builtin_amdgcn_wave_barrier(); __builtin_amdgcn_fence(__ATOMIC_ACQUIRE, "wavefront");
;     { const int n8 = lane >> 3, k8 = (lane & 7) * 8;
; #pragma unroll
;       for (int i = 0; i < 8; ++i) { const int n = 8 * i + n8; const float* sp = T + k8 * 65 + n;
;           u32x4 o; o.x = cvt_pk_bf16(sp[0], sp[65]); o.y = cvt_pk_bf16(sp[2 * 65], sp[3 * 65]); o.z = cvt_pk_bf16(sp[4 * 65], sp[5 * 65]); o.w = cvt_pk_bf16(sp[6 * 65], sp[7 * 65]);
;           *(u32x4*)(WT + (size_t)(n0 + n) * K + k0 + k8) = o; } }
;     __builtin_amdgcn_fence(__ATOMIC_RELEASE, "wavefront"); __builtin_amdgcn_wave_barrier(); __builtin_amdgcn_fence(__ATOMIC_ACQUIRE, "wavefront");
	ds_write2_b32 v60, v112, v113 offset1:1
	v_add_u32_e32 v60, 0xc38, v4
	ds_write2_b32 v60, v114, v115 offset1:1
	v_add_u32_e32 v60, 0x1040, v4
	s_waitcnt vmcnt(1)
	ds_write2_b32 v60, v116, v117 offset1:1
	v_add_u32_e32 v60, 0x1048, v4
	ds_write2_b32 v60, v118, v119 offset1:1
	v_add_u32_e32 v60, 0x1450, v4
	v_add_u32_e32 v4, 0x1458, v4
	s_waitcnt vmcnt(0)
	ds_write2_b32 v4, v122, v123 offset1:1
	v_lshlrev_b32_e32 v4, 1, v59
	v_add_u32_e32 v59, 0x400, v48
	ds_write2_b32 v60, v120, v121 offset1:1
	ds_read2_b32 v[64:65], v48 offset0:65 offset1:73
	ds_read2_b32 v[66:67], v48 offset1:8
	ds_read2_b32 v[68:69], v48 offset0:130 offset1:138
	ds_read2_b32 v[70:71], v48 offset0:195 offset1:203
	ds_read2_b32 v[72:73], v59 offset0:4 offset1:12
	ds_read2_b32 v[74:75], v59 offset0:69 offset1:77
	ds_read2_b32 v[76:77], v59 offset0:134 offset1:142
	ds_read2_b32 v[78:79], v59 offset0:199 offset1:207
	v_lshl_add_u64 v[80:81], v[22:23], 0, v[4:5]
	v_or_b32_e32 v4, v124, v47
	v_lshlrev_b32_e32 v4, 12, v4
	v_lshl_add_u64 v[82:83], v[80:81], 0, v[4:5]
	s_waitcnt lgkmcnt(6)
	v_cvt_pk_bf16_f32 v60, v66, v64
	s_waitcnt lgkmcnt(4)
	v_cvt_pk_bf16_f32 v61, v68, v70
	s_waitcnt lgkmcnt(2)
	v_cvt_pk_bf16_f32 v62, v72, v74
	s_waitcnt lgkmcnt(0)
	v_cvt_pk_bf16_f32 v63, v76, v78
	global_store_dwordx4 v[82:83], v[60:63], off
	v_or_b32_e32 v4, v124, v49
	v_lshlrev_b32_e32 v4, 12, v4
	v_cvt_pk_bf16_f32 v60, v67, v65
	v_cvt_pk_bf16_f32 v61, v69, v71
	v_cvt_pk_bf16_f32 v62, v73, v75
	v_cvt_pk_bf16_f32 v63, v77, v79
	ds_read2_b32 v[66:67], v48 offset0:16 offset1:24
	ds_read2_b32 v[68:69], v48 offset0:81 offset1:89
	ds_read2_b32 v[70:71], v48 offset0:146 offset1:154
	ds_read2_b32 v[72:73], v48 offset0:211 offset1:219
	ds_read2_b32 v[74:75], v59 offset0:20 offset1:28
	ds_read2_b32 v[76:77], v59 offset0:85 offset1:93
	ds_read2_b32 v[78:79], v59 offset0:150 offset1:158
	ds_read2_b32 v[82:83], v59 offset0:215 offset1:223
	v_lshl_add_u64 v[64:65], v[80:81], 0, v[4:5]
	v_or_b32_e32 v4, v124, v50
	v_lshlrev_b32_e32 v4, 12, v4
	global_store_dwordx4 v[64:65], v[60:63], off
	v_lshl_add_u64 v[64:65], v[80:81], 0, v[4:5]
	v_or_b32_e32 v4, v124, v51
	s_waitcnt lgkmcnt(6)
	v_cvt_pk_bf16_f32 v60, v66, v68
	s_waitcnt lgkmcnt(4)
	v_cvt_pk_bf16_f32 v61, v70, v72
	s_waitcnt lgkmcnt(2)
	v_cvt_pk_bf16_f32 v62, v74, v76
	s_waitcnt lgkmcnt(0)
	v_cvt_pk_bf16_f32 v63, v78, v82
	global_store_dwordx4 v[64:65], v[60:63], off
	v_lshlrev_b32_e32 v4, 12, v4
	v_lshl_add_u64 v[64:65], v[80:81], 0, v[4:5]
	v_cvt_pk_bf16_f32 v60, v67, v69
	v_cvt_pk_bf16_f32 v61, v71, v73
	v_cvt_pk_bf16_f32 v62, v75, v77
	v_cvt_pk_bf16_f32 v63, v79, v83
	ds_read2_b32 v[66:67], v48 offset0:32 offset1:40
	ds_read2_b32 v[68:69], v48 offset0:97 offset1:105
	ds_read2_b32 v[70:71], v48 offset0:162 offset1:170
	ds_read2_b32 v[72:73], v48 offset0:227 offset1:235
	ds_read2_b32 v[74:75], v59 offset0:36 offset1:44
	ds_read2_b32 v[76:77], v59 offset0:101 offset1:109
	ds_read2_b32 v[78:79], v59 offset0:166 offset1:174
	ds_read2_b32 v[82:83], v59 offset0:231 offset1:239
	v_or_b32_e32 v4, v124, v52
	v_lshlrev_b32_e32 v4, 12, v4
	global_store_dwordx4 v[64:65], v[60:63], off
	v_lshl_add_u64 v[64:65], v[80:81], 0, v[4:5]
	v_or_b32_e32 v4, v124, v53
	s_waitcnt lgkmcnt(6)
	v_cvt_pk_bf16_f32 v60, v66, v68
	s_waitcnt lgkmcnt(4)
	v_cvt_pk_bf16_f32 v61, v70, v72
	s_waitcnt lgkmcnt(2)
	v_cvt_pk_bf16_f32 v62, v74, v76
	s_waitcnt lgkmcnt(0)
	v_cvt_pk_bf16_f32 v63, v78, v82
	global_store_dwordx4 v[64:65], v[60:63], off
	v_lshlrev_b32_e32 v4, 12, v4
	v_lshl_add_u64 v[64:65], v[80:81], 0, v[4:5]
	v_cvt_pk_bf16_f32 v60, v67, v69
	v_cvt_pk_bf16_f32 v61, v71, v73
	v_cvt_pk_bf16_f32 v62, v75, v77
	v_cvt_pk_bf16_f32 v63, v79, v83
	ds_read2_b32 v[66:67], v48 offset0:48 offset1:56
	ds_read2_b32 v[68:69], v48 offset0:113 offset1:121
	ds_read2_b32 v[70:71], v48 offset0:178 offset1:186
	ds_read2_b32 v[72:73], v48 offset0:243 offset1:251
	ds_read2_b32 v[74:75], v59 offset0:52 offset1:60
	ds_read2_b32 v[76:77], v59 offset0:117 offset1:125
	ds_read2_b32 v[78:79], v59 offset0:182 offset1:190
	ds_read2_b32 v[82:83], v59 offset0:247 offset1:255
	v_or_b32_e32 v4, v124, v54
	v_lshlrev_b32_e32 v4, 12, v4
	global_store_dwordx4 v[64:65], v[60:63], off
	v_lshl_add_u64 v[64:65], v[80:81], 0, v[4:5]
	v_or_b32_e32 v4, v124, v55
	v_lshlrev_b32_e32 v4, 12, v4
	s_waitcnt lgkmcnt(6)
	v_cvt_pk_bf16_f32 v60, v66, v68
	s_waitcnt lgkmcnt(4)
	v_cvt_pk_bf16_f32 v61, v70, v72
	s_waitcnt lgkmcnt(2)
	v_cvt_pk_bf16_f32 v62, v74, v76
	s_waitcnt lgkmcnt(0)
	v_cvt_pk_bf16_f32 v63, v78, v82
	global_store_dwordx4 v[64:65], v[60:63], off
	v_lshl_add_u64 v[64:65], v[80:81], 0, v[4:5]
	s_nop 0
	v_cvt_pk_bf16_f32 v60, v67, v69
	v_cvt_pk_bf16_f32 v61, v71, v73
	v_cvt_pk_bf16_f32 v62, v75, v77
	v_cvt_pk_bf16_f32 v63, v79, v83
	global_store_dwordx4 v[64:65], v[60:63], off

; __device__ __forceinline__ void convT_tile(const float* __restrict__ W, int K, int N, bf16_t* __restrict__ WT, int tile, unsigned char* shm, int wave, int lane) {
;     const int ntn = N / 64, k0 = (tile / ntn) * 64, n0 = (tile % ntn) * 64;
;     float* T = (float*)shm + wave * (64 * 65);
;     { const int r4 = lane >> 4, c4 = (lane & 15) * 4;
; #pragma unroll
;       for (int i = 0; i < 16; ++i) { const int rr = 4 * i + r4; const float4 v = *(const float4*)(W + (size_t)(k0 + rr) * N + n0 + c4);
;           T[rr * 65 + c4] = v.x; T[rr * 65 + c4 + 1] = v.y; T[rr * 65 + c4 + 2] = v.z; T[rr * 65 + c4 + 3] = v.w; } }
; __device__ __forceinline__ void phase_lprep(PRef p, int layer, unsigned char* shm, const float* hL_, const float* hC_) {
;     ...
;         if (r < T_IN) { convT_tile(p.in[7] + (size_t)layer * 2048 * 5120, 2048, 5120, (bf16_t*)(p.ws + O_WT_IN), r, shm, wave, lane); continue; } r -= T_IN;
.LBB0_763:
	s_andn2_saveexec_b64 s[10:11], s[10:11]
	s_cbranch_execz .LBB0_748
	v_mul_hi_i32 v4, v58, s25
	v_lshrrev_b32_e32 v59, 31, v4
	v_ashrrev_i32_e32 v4, 5, v4
	v_add_u32_e32 v4, v4, v59
	v_mad_u64_u32 v[126:127], s[16:17], v4, s26, v[26:27]
	v_lshlrev_b32_e32 v124, 6, v4
	v_ashrrev_i32_e32 v127, 31, v126
	v_lshl_add_u64 v[120:121], v[126:127], 2, v[24:25]
	v_or_b32_e32 v4, v124, v1
	v_mad_i64_i32 v[60:61], s[16:17], v4, s27, v[120:121]
	v_or_b32_e32 v4, v124, v29
	v_mad_i64_i32 v[64:65], s[16:17], v4, s27, v[120:121]
	v_or_b32_e32 v4, v124, v31
	v_mad_i64_i32 v[68:69], s[16:17], v4, s27, v[120:121]
	v_or_b32_e32 v4, v124, v32
	v_mad_i64_i32 v[72:73], s[16:17], v4, s27, v[120:121]
	v_or_b32_e32 v4, v124, v33
	global_load_dwordx4 v[60:63], v[60:61], off nt
	s_nop 0
	global_load_dwordx4 v[64:67], v[64:65], off nt
	s_nop 0
	global_load_dwordx4 v[68:71], v[68:69], off nt
	s_nop 0
	global_load_dwordx4 v[72:75], v[72:73], off nt
	v_mad_i64_i32 v[76:77], s[16:17], v4, s27, v[120:121]
	v_or_b32_e32 v4, v124, v34
	global_load_dwordx4 v[76:79], v[76:77], off nt
	v_mad_i64_i32 v[80:81], s[16:17], v4, s27, v[120:121]
	global_load_dwordx4 v[80:83], v[80:81], off nt
	v_or_b32_e32 v4, v124, v36
	v_mad_i64_i32 v[84:85], s[16:17], v4, s27, v[120:121]
	global_load_dwordx4 v[84:87], v[84:85], off nt
	v_or_b32_e32 v4, v124, v37
	v_mad_i64_i32 v[88:89], s[16:17], v4, s27, v[120:121]
	global_load_dwordx4 v[88:91], v[88:89], off nt
	v_or_b32_e32 v4, v124, v38
	v_mad_i64_i32 v[92:93], s[16:17], v4, s27, v[120:121]
	global_load_dwordx4 v[92:95], v[92:93], off nt
	v_or_b32_e32 v4, v124, v39
	v_mad_i64_i32 v[96:97], s[16:17], v4, s27, v[120:121]
	v_or_b32_e32 v4, v124, v40
	global_load_dwordx4 v[96:99], v[96:97], off nt
	v_mad_i64_i32 v[100:101], s[16:17], v4, s27, v[120:121]
	global_load_dwordx4 v[100:103], v[100:101], off nt
	v_or_b32_e32 v4, v124, v42
	v_mad_i64_i32 v[104:105], s[16:17], v4, s27, v[120:121]
	global_load_dwordx4 v[104:107], v[104:105], off nt
	v_or_b32_e32 v4, v124, v43
	v_mad_i64_i32 v[108:109], s[16:17], v4, s27, v[120:121]
	global_load_dwordx4 v[108:111], v[108:109], off nt
	v_or_b32_e32 v4, v124, v44
	v_mad_i64_i32 v[112:113], s[16:17], v4, s27, v[120:121]
	global_load_dwordx4 v[112:115], v[112:113], off nt
	v_or_b32_e32 v4, v124, v45
	v_mad_i64_i32 v[116:117], s[16:17], v4, s27, v[120:121]
	global_load_dwordx4 v[116:119], v[116:117], off nt
	v_or_b32_e32 v4, v124, v46
	v_mad_i64_i32 v[120:121], s[16:17], v4, s27, v[120:121]
	global_load_dwordx4 v[120:123], v[120:121], off nt
	v_add_u32_e32 v4, v3, v27
	v_add_u32_e32 v59, 0x410, v4
	v_add_u32_e32 v125, 0x418, v4
	v_add_u32_e32 v127, 0x820, v4
	v_add_u32_e32 v128, 0x828, v4
	v_add_u32_e32 v129, 0xc30, v4
	v_add_u32_e32 v130, 0xc38, v4
	s_waitcnt vmcnt(15)
	ds_write2_b32 v4, v60, v61 offset1:1
	ds_write2_b32 v4, v62, v63 offset0:2 offset1:3
	s_waitcnt vmcnt(14)
	ds_write2_b32 v59, v64, v65 offset1:1
	ds_write2_b32 v125, v66, v67 offset1:1
	s_waitcnt vmcnt(13)
	ds_write2_b32 v127, v68, v69 offset1:1
	ds_write2_b32 v128, v70, v71 offset1:1
	s_waitcnt vmcnt(12)
	ds_write2_b32 v129, v72, v73 offset1:1
	ds_write2_b32 v130, v74, v75 offset1:1
	v_add_u32_e32 v59, 0x1040, v4
	v_ashrrev_i32_e32 v125, 31, v124
	s_waitcnt vmcnt(11)
	ds_write2_b32 v59, v76, v77 offset1:1
	v_add_u32_e32 v59, 0x1048, v4
	v_add_u32_e32 v4, 0x1450, v4
	s_waitcnt vmcnt(10)
	ds_write2_b32 v4, v80, v81 offset1:1
	v_add_u32_e32 v4, v3, v35
	ds_write2_b32 v59, v78, v79 offset1:1
	v_add_u32_e32 v59, 0x410, v4
	s_waitcnt vmcnt(9)
	ds_write2_b32 v59, v84, v85 offset1:1
	v_add_u32_e32 v59, 0x418, v4
	ds_write2_b32 v59, v86, v87 offset1:1
	v_add_u32_e32 v59, 0x820, v4
	s_waitcnt vmcnt(8)
	ds_write2_b32 v59, v88, v89 offset1:1
	v_add_u32_e32 v59, 0x828, v4
	ds_write2_b32 v59, v90, v91 offset1:1
	v_add_u32_e32 v59, 0xc30, v4
	s_waitcnt vmcnt(7)
	ds_write2_b32 v59, v92, v93 offset1:1
	v_add_u32_e32 v59, 0xc38, v4
	ds_write2_b32 v59, v94, v95 offset1:1
	v_add_u32_e32 v59, 0x1040, v4
	ds_write2_b32 v4, v82, v83 offset0:2 offset1:3
	s_waitcnt vmcnt(6)
	ds_write2_b32 v59, v96, v97 offset1:1
	v_add_u32_e32 v59, 0x1048, v4
	v_add_u32_e32 v4, 0x1450, v4
	s_waitcnt vmcnt(5)
	ds_write2_b32 v4, v100, v101 offset1:1
	v_add_u32_e32 v4, v3, v41
	ds_write2_b32 v59, v98, v99 offset1:1
	v_add_u32_e32 v59, 0x410, v4
	s_waitcnt vmcnt(4)
	ds_write2_b32 v59, v104, v105 offset1:1
	v_add_u32_e32 v59, 0x418, v4
	ds_write2_b32 v59, v106, v107 offset1:1
	v_add_u32_e32 v59, 0x820, v4
	s_waitcnt vmcnt(3)
	ds_write2_b32 v59, v108, v109 offset1:1
	v_add_u32_e32 v59, 0x828, v4
	ds_write2_b32 v59, v110, v111 offset1:1
	v_add_u32_e32 v59, 0xc30, v4
	s_waitcnt vmcnt(2)
	ds_write2_b32 v59, v112, v113 offset1:1
	v_add_u32_e32 v59, 0xc38, v4
	ds_write2_b32 v59, v114, v115 offset1:1
	v_add_u32_e32 v59, 0x1040, v4
	s_waitcnt vmcnt(1)
; __device__ __forceinline__ unsigned cvt_pk_bf16(float lo, float hi) { unsigned r; asm("v_cvt_pk_bf16_f32 %0, %1, %2" : "=v"(r) : "v"(lo), "v"(hi)); return r; }
; __device__ __forceinline__ void convT_tile(const float* __restrict__ W, int K, int N, bf16_t* __restrict__ WT, int tile, unsigned char* shm, int wave, int lane) {
;     ...
;     __builtin_amdgcn_fence(__ATOMIC_RELEASE, "wavefront"); __builtin_amdgcn_wave_barrier(); __builtin_amdgcn_fence(__ATOMIC_ACQUIRE, "wavefront");
;     { const int n8 = lane >> 3, k8 = (lane & 7) * 8;
; #pragma unroll
;       for (int i = 0; i < 8; ++i) { const int n = 8 * i + n8; const float* sp = T + k8 * 65 + n;
;           u32x4 o; o.x = cvt_pk_bf16(sp[0], sp[65]); o.y = cvt_pk_bf16(sp[2 * 65], sp[3 * 65]); o.z = cvt_pk_bf16(sp[4 * 65], sp[5 * 65]); o.w = cvt_pk_bf16(sp[6 * 65], sp[7 * 65]);
;           *(u32x4*)(WT + (size_t)(n0 + n) * K + k0 + k8) = o; } }
;     __builtin_amdgcn_fence(__ATOMIC_RELEASE, "wavefront"); __builtin_amdgcn_wave_barrier(); __builtin_amdgcn_fence(__ATOMIC_ACQUIRE, "wavefront");
	ds_write2_b32 v59, v116, v117 offset1:1
	v_add_u32_e32 v59, 0x1048, v4
	ds_write2_b32 v4, v102, v103 offset0:2 offset1:3
	ds_write2_b32 v59, v118, v119 offset1:1
	v_add_u32_e32 v59, 0x1450, v4
	v_add_u32_e32 v4, 0x1458, v4
	s_waitcnt vmcnt(0)
	ds_write2_b32 v4, v122, v123 offset1:1
	v_add_u32_e32 v4, 0x400, v48
	ds_write2_b32 v59, v120, v121 offset1:1
	ds_read2_b32 v[64:65], v48 offset0:65 offset1:73
	ds_read2_b32 v[66:67], v48 offset1:8
	ds_read2_b32 v[68:69], v48 offset0:130 offset1:138
	ds_read2_b32 v[70:71], v48 offset0:195 offset1:203
	ds_read2_b32 v[72:73], v4 offset0:4 offset1:12
	ds_read2_b32 v[74:75], v4 offset0:69 offset1:77
	ds_read2_b32 v[76:77], v4 offset0:134 offset1:142
	ds_read2_b32 v[78:79], v4 offset0:199 offset1:207
	v_add_u32_e32 v82, v126, v47
	v_ashrrev_i32_e32 v83, 31, v82
	v_lshl_add_u64 v[80:81], v[124:125], 1, v[8:9]
	v_lshlrev_b64 v[84:85], 12, v[82:83]
	s_waitcnt lgkmcnt(6)
	v_cvt_pk_bf16_f32 v60, v66, v64
	v_lshl_add_u64 v[84:85], v[80:81], 0, v[84:85]
	v_add_u32_e32 v64, 8, v82
	s_waitcnt lgkmcnt(4)
	v_cvt_pk_bf16_f32 v61, v68, v70
	s_waitcnt lgkmcnt(2)
	v_cvt_pk_bf16_f32 v62, v72, v74
	s_waitcnt lgkmcnt(0)
	v_cvt_pk_bf16_f32 v63, v76, v78
	global_store_dwordx4 v[84:85], v[60:63], off
	s_nop 1
	v_cvt_pk_bf16_f32 v60, v67, v65
	v_ashrrev_i32_e32 v65, 31, v64
	v_lshlrev_b64 v[64:65], 12, v[64:65]
	v_cvt_pk_bf16_f32 v61, v69, v71
	v_cvt_pk_bf16_f32 v62, v73, v75
	v_cvt_pk_bf16_f32 v63, v77, v79
	v_lshl_add_u64 v[64:65], v[80:81], 0, v[64:65]
	ds_read2_b32 v[66:67], v48 offset0:16 offset1:24
	ds_read2_b32 v[68:69], v48 offset0:81 offset1:89
	ds_read2_b32 v[70:71], v48 offset0:146 offset1:154
	ds_read2_b32 v[72:73], v48 offset0:211 offset1:219
	ds_read2_b32 v[74:75], v4 offset0:20 offset1:28
	ds_read2_b32 v[76:77], v4 offset0:85 offset1:93
	ds_read2_b32 v[78:79], v4 offset0:150 offset1:158
	ds_read2_b32 v[84:85], v4 offset0:215 offset1:223
	global_store_dwordx4 v[64:65], v[60:63], off
	v_add_u32_e32 v64, 16, v82
	v_ashrrev_i32_e32 v65, 31, v64
	v_lshlrev_b64 v[64:65], 12, v[64:65]
	v_lshl_add_u64 v[64:65], v[80:81], 0, v[64:65]
	s_waitcnt lgkmcnt(6)
	v_cvt_pk_bf16_f32 v60, v66, v68
	s_waitcnt lgkmcnt(4)
	v_cvt_pk_bf16_f32 v61, v70, v72
	s_waitcnt lgkmcnt(2)
	v_cvt_pk_bf16_f32 v62, v74, v76
	s_waitcnt lgkmcnt(0)
	v_cvt_pk_bf16_f32 v63, v78, v84
	global_store_dwordx4 v[64:65], v[60:63], off
	v_add_u32_e32 v64, 24, v82
	v_ashrrev_i32_e32 v65, 31, v64
	v_lshlrev_b64 v[64:65], 12, v[64:65]
	v_cvt_pk_bf16_f32 v60, v67, v69
	v_cvt_pk_bf16_f32 v61, v71, v73
	v_cvt_pk_bf16_f32 v62, v75, v77
	v_cvt_pk_bf16_f32 v63, v79, v85
	v_lshl_add_u64 v[64:65], v[80:81], 0, v[64:65]
	ds_read2_b32 v[66:67], v48 offset0:32 offset1:40
	ds_read2_b32 v[68:69], v48 offset0:97 offset1:105
	ds_read2_b32 v[70:71], v48 offset0:162 offset1:170
	ds_read2_b32 v[72:73], v48 offset0:227 offset1:235
	ds_read2_b32 v[74:75], v4 offset0:36 offset1:44
	ds_read2_b32 v[76:77], v4 offset0:101 offset1:109
	ds_read2_b32 v[78:79], v4 offset0:166 offset1:174
	ds_read2_b32 v[84:85], v4 offset0:231 offset1:239
	global_store_dwordx4 v[64:65], v[60:63], off
	v_add_u32_e32 v64, 32, v82
	v_ashrrev_i32_e32 v65, 31, v64
	v_lshlrev_b64 v[64:65], 12, v[64:65]
	v_lshl_add_u64 v[64:65], v[80:81], 0, v[64:65]
	s_waitcnt lgkmcnt(6)
	v_cvt_pk_bf16_f32 v60, v66, v68
	s_waitcnt lgkmcnt(4)
	v_cvt_pk_bf16_f32 v61, v70, v72
	s_waitcnt lgkmcnt(2)
	v_cvt_pk_bf16_f32 v62, v74, v76
	s_waitcnt lgkmcnt(0)
	v_cvt_pk_bf16_f32 v63, v78, v84
	global_store_dwordx4 v[64:65], v[60:63], off
	v_add_u32_e32 v64, 40, v82
	v_ashrrev_i32_e32 v65, 31, v64
	v_lshlrev_b64 v[64:65], 12, v[64:65]
	v_cvt_pk_bf16_f32 v60, v67, v69
	v_cvt_pk_bf16_f32 v61, v71, v73
	v_cvt_pk_bf16_f32 v62, v75, v77
	v_cvt_pk_bf16_f32 v63, v79, v85
	v_lshl_add_u64 v[64:65], v[80:81], 0, v[64:65]
	ds_read2_b32 v[66:67], v48 offset0:48 offset1:56
	ds_read2_b32 v[68:69], v48 offset0:113 offset1:121
	ds_read2_b32 v[70:71], v48 offset0:178 offset1:186
	ds_read2_b32 v[72:73], v48 offset0:243 offset1:251
	ds_read2_b32 v[74:75], v4 offset0:52 offset1:60
	ds_read2_b32 v[76:77], v4 offset0:117 offset1:125
	ds_read2_b32 v[78:79], v4 offset0:182 offset1:190
	ds_read2_b32 v[84:85], v4 offset0:247 offset1:255
	global_store_dwordx4 v[64:65], v[60:63], off
	v_add_u32_e32 v64, 48, v82
	v_ashrrev_i32_e32 v65, 31, v64
	v_lshlrev_b64 v[64:65], 12, v[64:65]
	v_lshl_add_u64 v[64:65], v[80:81], 0, v[64:65]
	s_waitcnt lgkmcnt(6)
	v_cvt_pk_bf16_f32 v60, v66, v68
	s_waitcnt lgkmcnt(4)
	v_cvt_pk_bf16_f32 v61, v70, v72
	s_waitcnt lgkmcnt(2)
	v_cvt_pk_bf16_f32 v62, v74, v76
	s_waitcnt lgkmcnt(0)
	v_cvt_pk_bf16_f32 v63, v78, v84
	global_store_dwordx4 v[64:65], v[60:63], off
	v_add_u32_e32 v64, 56, v82
	v_ashrrev_i32_e32 v65, 31, v64
	v_lshlrev_b64 v[64:65], 12, v[64:65]
	v_lshl_add_u64 v[64:65], v[80:81], 0, v[64:65]
	v_cvt_pk_bf16_f32 v60, v67, v69
	v_cvt_pk_bf16_f32 v61, v71, v73
	v_cvt_pk_bf16_f32 v62, v75, v77
	v_cvt_pk_bf16_f32 v63, v79, v85
	global_store_dwordx4 v[64:65], v[60:63], off
	s_branch .LBB0_748
